# UP epilogue: per-tile bias/conv/ss parameters prefetched into spare LDS by LDS-DMA in the tile prologue, read back with ds_read
# speedup vs baseline: 1.0131x; 1.0020x over previous
; #define LAS __attribute__((address_space(3)))
; __global__ void __launch_bounds__(NTHR, 2) mega(Params p) {
;     extern __shared__ __attribute__((aligned(16))) unsigned char lds[];
;     cg::grid_group grid = cg::this_grid();
;     const int G = gridDim.x, bid = blockIdx.x;
;     const int wv = __builtin_amdgcn_readfirstlane(threadIdx.x >> 6);
;     volatile LAS unsigned* xst = (volatile LAS unsigned*)((LAS unsigned char*)lds + (LDS_BYTES - 16));
;     if (threadIdx.x == 0) { xst[0] = 0u; xst[1] = 0u; }
;     __syncthreads();
_Z4mega6Params:
	s_mov_b32 s98, 0x20000
	s_load_dwordx16 s[16:31], s[0:1], 0x80
	s_load_dword s62, s[0:1], 0xc8
	s_load_dwordx2 s[34:35], s[0:1], 0xc0
	s_add_u32 s6, s0, 0xc0
	v_and_b32_e32 v1, 0x3ff, v0
	s_addc_u32 s7, s1, 0
	v_readfirstlane_b32 s3, v1
	v_cmp_eq_u32_e32 vcc, 0, v1
	s_and_saveexec_b64 s[4:5], vcc
	s_cbranch_execz .LBB0_2
	s_add_i32 s8, 0, 0x23ff0
	v_mov_b32_e32 v2, 0
	v_mov_b32_e32 v3, s8
	s_add_i32 s8, 0, 0x23ff4
	ds_write_b32 v3, v2
	v_mov_b32_e32 v3, s8
	ds_write_b32 v3, v2

;     __device__ __forceinline__ void operator()(const f32x4 (&acc)[2][2][4][2], const Unit& u, int wr, int wc, int fr, int fq) const {
;     ...
;         const int row0 = u.pm * BM + wr * 64 + fr, colt = u.pn * BM + wc * 32 + 8 * fq;
;         const int seq = seq_of_row(u.pm * BM);
;         const float* biasp = bias + (size_t)seq * NUP + colt; const float* cwp = cw + colt;
;         float rs[2][4];
; #pragma unroll
;         for (int ai = 0; ai < 2; ++ai)
; #pragma unroll
;             for (int m = 0; m < 4; ++m) rs[ai][m] = (float)ssin[row0 + ai * HALF + m * 16];
; #pragma unroll
;         for (int ai = 0; ai < 2; ++ai)
; #pragma unroll
;             for (int m = 0; m < 4; ++m) rs[ai][m] = __builtin_amdgcn_rsqf(rs[ai][m] * SSKI + EPSN);
; #pragma unroll
;         for (int n = 0; n < 2; ++n) {
;             f32x4 prm[2][5];
; #pragma unroll
;             for (int bj = 0; bj < 2; ++bj) { const int co = bj * HALF + 4 * n;
;                 prm[bj][0] = *(const f32x4*)(biasp + co); prm[bj][1] = *(const f32x4*)(cwp + co); prm[bj][2] = *(const f32x4*)(cwp + NUP + co); prm[bj][3] = *(const f32x4*)(cwp + 2 * NUP + co); prm[bj][4] = *(const f32x4*)(cwp + 3 * NUP + co); }
.LBB0_454:
	s_xor_b32 s98, s98, 0x2000
	s_cmp_gt_u32 s33, 6
	s_cbranch_scc1 .Lup_pf_done
	s_lshl_b32 s99, s12, 8
	s_cmpk_lt_u32 s99, 0x4000
	s_movk_i32 s100, 0x2c00
	s_cselect_b32 s100, 0x1600, s100
	s_cmp_gt_i32 s12, 31
	s_cselect_b32 s100, s100, 0
	s_lshl_b32 s100, s100, 2
	s_add_u32 s100, s48, s100
	s_addc_u32 s101, s49, 0
	s_cmp_eq_u32 s33, 0
	s_cbranch_scc1 .Lup_pf_col
	s_add_i32 s99, s33, -1
	s_mul_i32 s99, s99, 0x5800
	s_add_u32 s100, s68, s99
	s_addc_u32 s101, s69, 0
	s_cmp_lt_u32 s33, 5
	s_cbranch_scc1 .Lup_pf_col
	s_lshl_b32 s99, s12, 11
	s_add_u32 s100, s22, s99
	s_addc_u32 s101, s23, 0
	s_sub_i32 s99, s33, 5
	s_lshl_b32 s99, s99, 10
	s_add_u32 s100, s100, s99
	s_addc_u32 s101, s101, 0
	s_branch .Lup_pf_go
.Lup_pf_col:
	s_lshl_b32 s99, s36, 10
	s_add_u32 s100, s100, s99
	s_addc_u32 s101, s101, 0
.Lup_pf_go:
	v_mbcnt_lo_u32_b32 v2, -1, 0
	v_mbcnt_hi_u32_b32 v2, -1, v2
	v_lshlrev_b32_e32 v2, 4, v2
	v_mov_b32_e32 v3, s101
	v_add_co_u32_e32 v2, vcc, s100, v2
	s_lshl_b32 s99, s33, 10
	v_addc_co_u32_e32 v3, vcc, 0, v3, vcc
	s_add_i32 m0, s98, s99
	s_nop 0
	global_load_lds_dwordx4 v[2:3], off

; #define PG8_STAGE(bufoff, gbase, voff) do { _Pragma("unroll") for (int _i = 0; _i < 2; ++_i) \
;         __builtin_amdgcn_global_load_lds((const unsigned*)((const char*)(gbase) + (voff)[_i]), (LAS unsigned*)(lds + (bufoff) + ldsw + _i * 8192), 16, 0, 0); } while (0)
; #define PG8_LDA(dst, b, h) do { _Pragma("unroll") for (int m = 0; m < 4; ++m) _Pragma("unroll") for (int k = 0; k < 2; ++k) dst[m][k] = *(const LAS bf16x8*)(lds + PG8_SA(b, h) + aoff + m * 2048 + k * 1024); } while (0)
; #define PG8_LDB(dst, b, h) do { _Pragma("unroll") for (int n = 0; n < 2; ++n) _Pragma("unroll") for (int k = 0; k < 2; ++k) dst[n][k] = *(const LAS bf16x8*)(lds + PG8_SB(b, h) + boff + n * 2048 + k * 1024); } while (0)
; #define PG8_MMA(ai, bj, At, Bt) do { __builtin_amdgcn_s_setprio(1); _Pragma("unroll") for (int m = 0; m < 4; ++m) _Pragma("unroll") for (int n = 0; n < 2; ++n) _Pragma("unroll") for (int k = 0; k < 2; ++k) \
;         acc[ai][bj][m][n] = __builtin_amdgcn_mfma_f32_16x16x32_bf16(Bt[n][k], At[m][k], acc[ai][bj][m][n], 0, 0, 0); __builtin_amdgcn_s_setprio(0); } while (0)
; #define PG8_WAIT_V(n) asm volatile("s_waitcnt vmcnt(" #n ")" ::: "memory")
; #define PG8_WAIT_L(n) asm volatile("s_waitcnt lgkmcnt(" #n ")" ::: "memory")
; #define PG8_BAR __builtin_amdgcn_s_barrier()
; #define PG8_SCHED __builtin_amdgcn_sched_barrier(0)
; template <class Epi>
; __device__ __forceinline__ void gemm_phase(int wv, LAS unsigned char* lds, const Gemm g, const StaticOrder& S, const Epi& E) {
;     ...
;             PG8_LDB(B0, 0, 0); PG8_SCHED; PG8_LDA(At, 0, 0); PG8_STAGE(PG8_SA(1, 1), a1 + hstepA, voffA);
;             PG8_WAIT_L(8); PG8_BAR; PG8_WAIT_L(0); PG8_MMA(0, 0, At, B0); PG8_BAR; PG8_SCHED;
;             PG8_LDB(B1, 0, 1); PG8_STAGE(PG8_SB(0, 0), b2, voffB);
;             PG8_BAR; PG8_WAIT_L(0); PG8_MMA(0, 1, At, B1); PG8_BAR;
;             PG8_LDA(At, 0, 1); PG8_STAGE(PG8_SA(0, 0), a2, voffA);
;             PG8_BAR; PG8_WAIT_L(0); PG8_MMA(1, 0, At, B0); PG8_BAR; PG8_SCHED;
;             PG8_STAGE(PG8_SB(0, 1), b2 + hstepB, voffB);
;             PG8_WAIT_V(6); PG8_BAR; PG8_MMA(1, 1, At, B1); PG8_BAR;
.LBB0_455:
	s_add_u32 s6, s4, 0xfffc0080
	s_addc_u32 s7, s5, -1
	s_add_i32 s42, 0, 0x10000
	v_add_u32_e32 v110, s42, v1
	ds_read_b128 v[98:101], v110
	ds_read_b128 v[102:105], v110 offset:1024
	ds_read_b128 v[106:109], v110 offset:2048
	ds_read_b128 v[110:113], v110 offset:3072
	s_cmp_eq_u32 s17, 12
	s_cselect_b32 s9, s10, s7
	s_cselect_b32 s8, s11, s6
	s_cselect_b32 s7, s13, s16
	s_cselect_b32 s6, s14, s15
	v_lshl_add_u64 v[192:193], s[4:5], 0, v[180:181]
	s_add_i32 m0, s60, 0xc000
	ds_read_b128 v[114:117], v179
	ds_read_b128 v[118:121], v179 offset:1024
	ds_read_b128 v[122:125], v179 offset:2048
	ds_read_b128 v[126:129], v179 offset:3072
	ds_read_b128 v[138:141], v179 offset:4096
	ds_read_b128 v[162:165], v179 offset:5120
	ds_read_b128 v[184:187], v179 offset:6144
	ds_read_b128 v[188:191], v179 offset:7168
	global_load_lds_dwordx4 v[192:193], off
	v_lshl_add_u64 v[192:193], s[4:5], 0, v[182:183]
	s_add_i32 m0, s60, 0xe000
	s_nop 0
	global_load_lds_dwordx4 v[192:193], off
	s_waitcnt lgkmcnt(8)
	s_barrier
	s_waitcnt lgkmcnt(0)
	s_setprio 1
	s_waitcnt lgkmcnt(0)
	v_mfma_f32_16x16x32_bf16 v[146:149], v[98:101], v[114:117], v[146:149]
	v_mfma_f32_16x16x32_bf16 v[46:49], v[106:109], v[114:117], v[46:49]
	v_mfma_f32_16x16x32_bf16 v[134:137], v[98:101], v[122:125], v[134:137]
	v_mfma_f32_16x16x32_bf16 v[38:41], v[106:109], v[122:125], v[38:41]
	v_mfma_f32_16x16x32_bf16 v[130:133], v[98:101], v[138:141], v[130:133]
	v_mfma_f32_16x16x32_bf16 v[34:37], v[106:109], v[138:141], v[34:37]
	v_mfma_f32_16x16x32_bf16 v[142:145], v[98:101], v[184:187], v[142:145]
	v_mfma_f32_16x16x32_bf16 v[42:45], v[106:109], v[184:187], v[42:45]
	v_mfma_f32_16x16x32_bf16 v[146:149], v[102:105], v[118:121], v[146:149]
	v_mfma_f32_16x16x32_bf16 v[46:49], v[110:113], v[118:121], v[46:49]
	v_mfma_f32_16x16x32_bf16 v[134:137], v[102:105], v[126:129], v[134:137]
	v_mfma_f32_16x16x32_bf16 v[38:41], v[110:113], v[126:129], v[38:41]
	v_mfma_f32_16x16x32_bf16 v[130:133], v[102:105], v[162:165], v[130:133]
	v_mfma_f32_16x16x32_bf16 v[34:37], v[110:113], v[162:165], v[34:37]
	v_mfma_f32_16x16x32_bf16 v[142:145], v[102:105], v[188:191], v[142:145]
	v_mfma_f32_16x16x32_bf16 v[42:45], v[110:113], v[188:191], v[42:45]
	s_setprio 0
	s_barrier
	s_add_i32 s44, 0, 0x14000
	s_add_i32 s42, s42, s59
	v_add_u32_e32 v204, s44, v1
	v_lshl_add_u64 v[212:213], s[6:7], 0, v[174:175]
	s_mov_b32 m0, s42
	ds_read_b128 v[192:195], v204
	ds_read_b128 v[196:199], v204 offset:1024
	ds_read_b128 v[200:203], v204 offset:2048
	ds_read_b128 v[204:207], v204 offset:3072
	global_load_lds_dwordx4 v[212:213], off
	v_lshl_add_u64 v[214:215], s[6:7], 0, v[170:171]
	s_add_i32 m0, s42, 0x2000
	s_nop 0
	global_load_lds_dwordx4 v[214:215], off
	s_barrier
	s_waitcnt lgkmcnt(0)
	s_setprio 1
	s_waitcnt lgkmcnt(0)
	v_mfma_f32_16x16x32_bf16 v[166:169], v[192:195], v[114:117], v[166:169]
	v_mfma_f32_16x16x32_bf16 v[62:65], v[200:203], v[114:117], v[62:65]
	v_mfma_f32_16x16x32_bf16 v[54:57], v[200:203], v[122:125], v[54:57]
	v_mfma_f32_16x16x32_bf16 v[50:53], v[200:203], v[138:141], v[50:53]
	v_mfma_f32_16x16x32_bf16 v[58:61], v[200:203], v[184:187], v[58:61]
	v_mfma_f32_16x16x32_bf16 v[166:169], v[196:199], v[118:121], v[166:169]
	v_mfma_f32_16x16x32_bf16 v[62:65], v[204:207], v[118:121], v[62:65]
	v_mfma_f32_16x16x32_bf16 v[114:117], v[192:195], v[122:125], v[154:157]
	v_mfma_f32_16x16x32_bf16 v[54:57], v[204:207], v[126:129], v[54:57]
	v_mfma_f32_16x16x32_bf16 v[118:121], v[192:195], v[138:141], v[150:153]
	v_mfma_f32_16x16x32_bf16 v[50:53], v[204:207], v[162:165], v[50:53]
	v_mfma_f32_16x16x32_bf16 v[122:125], v[192:195], v[184:187], v[158:161]
	v_mfma_f32_16x16x32_bf16 v[58:61], v[204:207], v[188:191], v[58:61]
	v_mfma_f32_16x16x32_bf16 v[114:117], v[196:199], v[126:129], v[114:117]
	v_mfma_f32_16x16x32_bf16 v[118:121], v[196:199], v[162:165], v[118:121]
	v_mfma_f32_16x16x32_bf16 v[122:125], v[196:199], v[188:191], v[122:125]
	s_setprio 0
	s_mov_b32 m0, s60
	v_lshl_add_u64 v[216:217], s[8:9], 0, v[176:177]
	s_barrier
	ds_read_b128 v[126:129], v179 offset:16384
	ds_read_b128 v[138:141], v179 offset:17408
	ds_read_b128 v[150:153], v179 offset:18432
	ds_read_b128 v[154:157], v179 offset:19456
	ds_read_b128 v[158:161], v179 offset:20480
	ds_read_b128 v[162:165], v179 offset:21504
	ds_read_b128 v[184:187], v179 offset:22528
	ds_read_b128 v[188:191], v179 offset:23552
	global_load_lds_dwordx4 v[216:217], off
	v_lshl_add_u64 v[218:219], s[8:9], 0, v[172:173]
	s_mov_b32 m0, s61
	s_nop 0
	global_load_lds_dwordx4 v[218:219], off
	s_barrier
	s_waitcnt lgkmcnt(0)
	s_setprio 1
	s_waitcnt lgkmcnt(0)
	v_mfma_f32_16x16x32_bf16 v[78:81], v[98:101], v[126:129], v[78:81]
	v_mfma_f32_16x16x32_bf16 v[14:17], v[106:109], v[126:129], v[14:17]
	v_mfma_f32_16x16x32_bf16 v[70:73], v[98:101], v[150:153], v[70:73]
	v_mfma_f32_16x16x32_bf16 v[6:9], v[106:109], v[150:153], v[6:9]
	v_mfma_f32_16x16x32_bf16 v[66:69], v[98:101], v[158:161], v[66:69]
	v_mfma_f32_16x16x32_bf16 v[2:5], v[106:109], v[158:161], v[2:5]
	v_mfma_f32_16x16x32_bf16 v[74:77], v[98:101], v[184:187], v[74:77]
	v_mfma_f32_16x16x32_bf16 v[10:13], v[106:109], v[184:187], v[10:13]
	v_mfma_f32_16x16x32_bf16 v[78:81], v[102:105], v[138:141], v[78:81]
	v_mfma_f32_16x16x32_bf16 v[14:17], v[110:113], v[138:141], v[14:17]
	v_mfma_f32_16x16x32_bf16 v[70:73], v[102:105], v[154:157], v[70:73]
	v_mfma_f32_16x16x32_bf16 v[6:9], v[110:113], v[154:157], v[6:9]
	v_mfma_f32_16x16x32_bf16 v[66:69], v[102:105], v[162:165], v[66:69]
	v_mfma_f32_16x16x32_bf16 v[2:5], v[110:113], v[162:165], v[2:5]
	v_mfma_f32_16x16x32_bf16 v[74:77], v[102:105], v[188:191], v[74:77]
	v_mfma_f32_16x16x32_bf16 v[10:13], v[110:113], v[188:191], v[10:13]
	s_setprio 0
	s_barrier
; #define PG8_STAGE(bufoff, gbase, voff) do { _Pragma("unroll") for (int _i = 0; _i < 2; ++_i) \
;         __builtin_amdgcn_global_load_lds((const unsigned*)((const char*)(gbase) + (voff)[_i]), (LAS unsigned*)(lds + (bufoff) + ldsw + _i * 8192), 16, 0, 0); } while (0)
; #define PG8_LDA(dst, b, h) do { _Pragma("unroll") for (int m = 0; m < 4; ++m) _Pragma("unroll") for (int k = 0; k < 2; ++k) dst[m][k] = *(const LAS bf16x8*)(lds + PG8_SA(b, h) + aoff + m * 2048 + k * 1024); } while (0)
; #define PG8_LDB(dst, b, h) do { _Pragma("unroll") for (int n = 0; n < 2; ++n) _Pragma("unroll") for (int k = 0; k < 2; ++k) dst[n][k] = *(const LAS bf16x8*)(lds + PG8_SB(b, h) + boff + n * 2048 + k * 1024); } while (0)
; #define PG8_MMA(ai, bj, At, Bt) do { __builtin_amdgcn_s_setprio(1); _Pragma("unroll") for (int m = 0; m < 4; ++m) _Pragma("unroll") for (int n = 0; n < 2; ++n) _Pragma("unroll") for (int k = 0; k < 2; ++k) \
;         acc[ai][bj][m][n] = __builtin_amdgcn_mfma_f32_16x16x32_bf16(Bt[n][k], At[m][k], acc[ai][bj][m][n], 0, 0, 0); __builtin_amdgcn_s_setprio(0); } while (0)
; #define PG8_WAIT_V(n) asm volatile("s_waitcnt vmcnt(" #n ")" ::: "memory")
; #define PG8_WAIT_L(n) asm volatile("s_waitcnt lgkmcnt(" #n ")" ::: "memory")
; #define PG8_BAR __builtin_amdgcn_s_barrier()
; #define PG8_SCHED __builtin_amdgcn_sched_barrier(0)
; template <class Epi>
; __device__ __forceinline__ void gemm_phase(int wv, LAS unsigned char* lds, const Gemm g, const StaticOrder& S, const Epi& E) {
;     ...
;             PG8_WAIT_V(6); PG8_BAR; PG8_MMA(1, 1, At, B1); PG8_BAR;
;             PG8_LDB(B0, 1, 0); PG8_SCHED; PG8_LDA(At, 1, 0); PG8_STAGE(PG8_SA(0, 1), a2 + hstepA, voffA);
;             PG8_WAIT_L(8); PG8_BAR; PG8_WAIT_L(0); PG8_MMA(0, 0, At, B0); PG8_BAR; PG8_SCHED;
;             PG8_LDB(B1, 1, 1); PG8_STAGE(PG8_SB(1, 0), b3, voffB);
;             PG8_BAR; PG8_WAIT_L(0); PG8_MMA(0, 1, At, B1); PG8_BAR;
;             PG8_LDA(At, 1, 1); PG8_STAGE(PG8_SA(1, 0), a3, voffA);
;             PG8_BAR; PG8_WAIT_L(0); PG8_MMA(1, 0, At, B0); PG8_BAR; PG8_SCHED;
	s_add_u32 s54, s6, 0x40000
	s_addc_u32 s55, s7, 0
	s_add_i32 s42, s44, s59
	v_lshl_add_u64 v[98:99], s[54:55], 0, v[174:175]
	s_mov_b32 m0, s42
	s_nop 0
	global_load_lds_dwordx4 v[98:99], off
	v_lshl_add_u64 v[98:99], s[54:55], 0, v[170:171]
	s_add_i32 m0, s42, 0x2000
	s_nop 0
	global_load_lds_dwordx4 v[98:99], off
	s_waitcnt vmcnt(6)
	s_barrier
	s_setprio 1
	v_mfma_f32_16x16x32_bf16 v[94:97], v[192:195], v[126:129], v[94:97]
	v_mfma_f32_16x16x32_bf16 v[30:33], v[200:203], v[126:129], v[30:33]
	v_mfma_f32_16x16x32_bf16 v[86:89], v[192:195], v[150:153], v[86:89]
	v_mfma_f32_16x16x32_bf16 v[26:29], v[200:203], v[150:153], v[26:29]
	v_mfma_f32_16x16x32_bf16 v[82:85], v[192:195], v[158:161], v[82:85]
	v_mfma_f32_16x16x32_bf16 v[18:21], v[200:203], v[158:161], v[18:21]
	v_mfma_f32_16x16x32_bf16 v[90:93], v[192:195], v[184:187], v[90:93]
	v_mfma_f32_16x16x32_bf16 v[22:25], v[200:203], v[184:187], v[22:25]
	v_mfma_f32_16x16x32_bf16 v[94:97], v[196:199], v[138:141], v[94:97]
	v_mfma_f32_16x16x32_bf16 v[30:33], v[204:207], v[138:141], v[30:33]
	v_mfma_f32_16x16x32_bf16 v[86:89], v[196:199], v[154:157], v[86:89]
	v_mfma_f32_16x16x32_bf16 v[26:29], v[204:207], v[154:157], v[26:29]
	v_mfma_f32_16x16x32_bf16 v[82:85], v[196:199], v[162:165], v[82:85]
	v_mfma_f32_16x16x32_bf16 v[18:21], v[204:207], v[162:165], v[18:21]
	v_mfma_f32_16x16x32_bf16 v[90:93], v[196:199], v[188:191], v[90:93]
	v_mfma_f32_16x16x32_bf16 v[22:25], v[204:207], v[188:191], v[22:25]
	s_setprio 0
	s_add_i32 s42, 0, 0x18000
	v_add_u32_e32 v110, s42, v1
	s_barrier
	ds_read_b128 v[98:101], v110
	ds_read_b128 v[102:105], v110 offset:1024
	ds_read_b128 v[106:109], v110 offset:2048
	ds_read_b128 v[110:113], v110 offset:3072
	s_add_u32 s8, s8, 0x40000
	s_addc_u32 s9, s9, 0
	s_mov_b32 m0, s64
	v_lshl_add_u64 v[154:155], s[8:9], 0, v[176:177]
	ds_read_b128 v[126:129], v179 offset:32768
	ds_read_b128 v[138:141], v179 offset:33792
	ds_read_b128 v[150:153], v179 offset:34816
	ds_read_b128 v[158:161], v179 offset:35840
	ds_read_b128 v[162:165], v179 offset:36864
	ds_read_b128 v[184:187], v179 offset:37888
	ds_read_b128 v[188:191], v179 offset:38912
	ds_read_b128 v[192:195], v179 offset:39936
	global_load_lds_dwordx4 v[154:155], off
	v_lshl_add_u64 v[154:155], s[8:9], 0, v[172:173]
	s_mov_b32 m0, s65
	s_nop 0
	global_load_lds_dwordx4 v[154:155], off
	s_waitcnt lgkmcnt(8)
	s_barrier
	s_waitcnt lgkmcnt(0)
	s_setprio 1
	s_waitcnt lgkmcnt(0)
	v_mfma_f32_16x16x32_bf16 v[146:149], v[98:101], v[126:129], v[146:149]
	v_mfma_f32_16x16x32_bf16 v[46:49], v[106:109], v[126:129], v[46:49]
	v_mfma_f32_16x16x32_bf16 v[134:137], v[98:101], v[150:153], v[134:137]
	v_mfma_f32_16x16x32_bf16 v[38:41], v[106:109], v[150:153], v[38:41]
	v_mfma_f32_16x16x32_bf16 v[130:133], v[98:101], v[162:165], v[130:133]
	v_mfma_f32_16x16x32_bf16 v[34:37], v[106:109], v[162:165], v[34:37]
	v_mfma_f32_16x16x32_bf16 v[142:145], v[98:101], v[188:191], v[142:145]
	v_mfma_f32_16x16x32_bf16 v[42:45], v[106:109], v[188:191], v[42:45]
	v_mfma_f32_16x16x32_bf16 v[146:149], v[102:105], v[138:141], v[146:149]
	v_mfma_f32_16x16x32_bf16 v[46:49], v[110:113], v[138:141], v[46:49]
	v_mfma_f32_16x16x32_bf16 v[134:137], v[102:105], v[158:161], v[134:137]
	v_mfma_f32_16x16x32_bf16 v[38:41], v[110:113], v[158:161], v[38:41]
	v_mfma_f32_16x16x32_bf16 v[130:133], v[102:105], v[184:187], v[130:133]
	v_mfma_f32_16x16x32_bf16 v[34:37], v[110:113], v[184:187], v[34:37]
	v_mfma_f32_16x16x32_bf16 v[142:145], v[102:105], v[192:195], v[142:145]
	v_mfma_f32_16x16x32_bf16 v[42:45], v[110:113], v[192:195], v[42:45]
	s_setprio 0
	s_barrier
	s_add_i32 s8, 0, 0x1c000
	v_add_u32_e32 v154, s8, v1
	s_add_i32 s9, s42, s59
	ds_read_b128 v[196:199], v154
	ds_read_b128 v[200:203], v154 offset:1024
	ds_read_b128 v[204:207], v154 offset:2048
	ds_read_b128 v[208:211], v154 offset:3072
	v_lshl_add_u64 v[154:155], v[212:213], 0, s[38:39]
	s_mov_b32 m0, s9
	s_nop 0
	global_load_lds_dwordx4 v[154:155], off
	v_lshl_add_u64 v[154:155], v[214:215], 0, s[38:39]
	s_add_i32 m0, s9, 0x2000
	s_nop 0
	global_load_lds_dwordx4 v[154:155], off
	s_barrier
	s_waitcnt lgkmcnt(0)
	s_setprio 1
	s_waitcnt lgkmcnt(0)
	v_mfma_f32_16x16x32_bf16 v[154:157], v[196:199], v[126:129], v[166:169]
	v_mfma_f32_16x16x32_bf16 v[114:117], v[196:199], v[150:153], v[114:117]
	v_mfma_f32_16x16x32_bf16 v[166:169], v[200:203], v[138:141], v[154:157]
	v_mfma_f32_16x16x32_bf16 v[154:157], v[200:203], v[158:161], v[114:117]
	v_mfma_f32_16x16x32_bf16 v[114:117], v[196:199], v[162:165], v[118:121]
	v_mfma_f32_16x16x32_bf16 v[62:65], v[204:207], v[126:129], v[62:65]
	v_mfma_f32_16x16x32_bf16 v[54:57], v[204:207], v[150:153], v[54:57]
	v_mfma_f32_16x16x32_bf16 v[150:153], v[200:203], v[184:187], v[114:117]
	v_mfma_f32_16x16x32_bf16 v[50:53], v[204:207], v[162:165], v[50:53]
	v_mfma_f32_16x16x32_bf16 v[114:117], v[196:199], v[188:191], v[122:125]
	v_mfma_f32_16x16x32_bf16 v[58:61], v[204:207], v[188:191], v[58:61]
	v_mfma_f32_16x16x32_bf16 v[62:65], v[208:211], v[138:141], v[62:65]
	v_mfma_f32_16x16x32_bf16 v[54:57], v[208:211], v[158:161], v[54:57]
	v_mfma_f32_16x16x32_bf16 v[50:53], v[208:211], v[184:187], v[50:53]
	v_mfma_f32_16x16x32_bf16 v[158:161], v[200:203], v[192:195], v[114:117]
	v_mfma_f32_16x16x32_bf16 v[58:61], v[208:211], v[192:195], v[58:61]
	s_setprio 0
	s_mov_b32 m0, s71
	v_lshl_add_u64 v[192:193], v[216:217], 0, s[38:39]
	s_barrier
	ds_read_b128 v[114:117], v179 offset:49152
	ds_read_b128 v[118:121], v179 offset:50176
	ds_read_b128 v[122:125], v179 offset:51200
	ds_read_b128 v[126:129], v179 offset:52224
	ds_read_b128 v[138:141], v179 offset:53248
	ds_read_b128 v[162:165], v179 offset:54272
	ds_read_b128 v[184:187], v179 offset:55296
	ds_read_b128 v[188:191], v179 offset:56320
	global_load_lds_dwordx4 v[192:193], off
	v_lshl_add_u64 v[192:193], v[218:219], 0, s[38:39]
	s_mov_b32 m0, s72
	s_nop 0
	global_load_lds_dwordx4 v[192:193], off
	s_barrier
; #define PG8_STAGE(bufoff, gbase, voff) do { _Pragma("unroll") for (int _i = 0; _i < 2; ++_i) \
;         __builtin_amdgcn_global_load_lds((const unsigned*)((const char*)(gbase) + (voff)[_i]), (LAS unsigned*)(lds + (bufoff) + ldsw + _i * 8192), 16, 0, 0); } while (0)
; #define PG8_WAIT_V(n) asm volatile("s_waitcnt vmcnt(" #n ")" ::: "memory")
; #define PG8_WAIT_L(n) asm volatile("s_waitcnt lgkmcnt(" #n ")" ::: "memory")
; template <class Epi>
; __device__ __forceinline__ void gemm_phase(int wv, LAS unsigned char* lds, const Gemm g, const StaticOrder& S, const Epi& E) {
;     ...
;             PG8_LDB(B0, 1, 0); PG8_SCHED; PG8_LDA(At, 1, 0); PG8_STAGE(PG8_SA(0, 1), a2 + hstepA, voffA);
;             PG8_WAIT_L(8); PG8_BAR; PG8_WAIT_L(0); PG8_MMA(0, 0, At, B0); PG8_BAR; PG8_SCHED;
;             PG8_LDB(B1, 1, 1); PG8_STAGE(PG8_SB(1, 0), b3, voffB);
;             PG8_BAR; PG8_WAIT_L(0); PG8_MMA(0, 1, At, B1); PG8_BAR;
;             PG8_LDA(At, 1, 1); PG8_STAGE(PG8_SA(1, 0), a3, voffA);
;             PG8_BAR; PG8_WAIT_L(0); PG8_MMA(1, 0, At, B0); PG8_BAR; PG8_SCHED;
;             PG8_STAGE(PG8_SB(1, 1), b3 + hstepB, voffB);
;             PG8_WAIT_V(6); PG8_BAR; PG8_MMA(1, 1, At, B1); PG8_BAR;
;         }
;     __device__ __forceinline__ void operator()(const f32x4 (&acc)[2][2][4][2], const Unit& u, int wr, int wc, int fr, int fq) const {
;     ...
;         const int row0 = u.pm * BM + wr * 64 + fr, colt = u.pn * BM + wc * 32 + 8 * fq;
;         const int seq = seq_of_row(u.pm * BM);
;         const float* biasp = bias + (size_t)seq * NUP + colt; const float* cwp = cw + colt;
;         float rs[2][4];
; #pragma unroll
;         for (int ai = 0; ai < 2; ++ai)
; #pragma unroll
;             for (int m = 0; m < 4; ++m) rs[ai][m] = (float)ssin[row0 + ai * HALF + m * 16];
; #pragma unroll
;         for (int ai = 0; ai < 2; ++ai)
; #pragma unroll
;             for (int m = 0; m < 4; ++m) rs[ai][m] = __builtin_amdgcn_rsqf(rs[ai][m] * SSKI + EPSN);
; #pragma unroll
;         for (int n = 0; n < 2; ++n) {
;             f32x4 prm[2][5];
; #pragma unroll
;             for (int bj = 0; bj < 2; ++bj) { const int co = bj * HALF + 4 * n;
;                 prm[bj][0] = *(const f32x4*)(biasp + co); prm[bj][1] = *(const f32x4*)(cwp + co); prm[bj][2] = *(const f32x4*)(cwp + NUP + co); prm[bj][3] = *(const f32x4*)(cwp + 2 * NUP + co); prm[bj][4] = *(const f32x4*)(cwp + 3 * NUP + co); }
	s_waitcnt lgkmcnt(0)
	s_setprio 1
	s_waitcnt lgkmcnt(0)
	v_mfma_f32_16x16x32_bf16 v[78:81], v[98:101], v[114:117], v[78:81]
	v_mfma_f32_16x16x32_bf16 v[14:17], v[106:109], v[114:117], v[14:17]
	v_mfma_f32_16x16x32_bf16 v[70:73], v[98:101], v[122:125], v[70:73]
	v_mfma_f32_16x16x32_bf16 v[6:9], v[106:109], v[122:125], v[6:9]
	v_mfma_f32_16x16x32_bf16 v[66:69], v[98:101], v[138:141], v[66:69]
	v_mfma_f32_16x16x32_bf16 v[2:5], v[106:109], v[138:141], v[2:5]
	v_mfma_f32_16x16x32_bf16 v[74:77], v[98:101], v[184:187], v[74:77]
	v_mfma_f32_16x16x32_bf16 v[10:13], v[106:109], v[184:187], v[10:13]
	v_mfma_f32_16x16x32_bf16 v[78:81], v[102:105], v[118:121], v[78:81]
	v_mfma_f32_16x16x32_bf16 v[14:17], v[110:113], v[118:121], v[14:17]
	v_mfma_f32_16x16x32_bf16 v[70:73], v[102:105], v[126:129], v[70:73]
	v_mfma_f32_16x16x32_bf16 v[6:9], v[110:113], v[126:129], v[6:9]
	v_mfma_f32_16x16x32_bf16 v[66:69], v[102:105], v[162:165], v[66:69]
	v_mfma_f32_16x16x32_bf16 v[2:5], v[110:113], v[162:165], v[2:5]
	v_mfma_f32_16x16x32_bf16 v[74:77], v[102:105], v[188:191], v[74:77]
	v_mfma_f32_16x16x32_bf16 v[10:13], v[110:113], v[188:191], v[10:13]
	s_setprio 0
	s_barrier
	s_add_u32 s6, s6, 0x40080
	s_addc_u32 s7, s7, 0
	s_add_i32 s8, s8, s59
	v_lshl_add_u64 v[98:99], s[6:7], 0, v[174:175]
	s_mov_b32 m0, s8
	s_nop 0
	global_load_lds_dwordx4 v[98:99], off
	v_lshl_add_u64 v[98:99], s[6:7], 0, v[170:171]
	s_add_i32 m0, s8, 0x2000
	s_nop 0
	global_load_lds_dwordx4 v[98:99], off
	s_waitcnt vmcnt(6)
	s_barrier
	s_setprio 1
	v_mfma_f32_16x16x32_bf16 v[94:97], v[196:199], v[114:117], v[94:97]
	v_mfma_f32_16x16x32_bf16 v[30:33], v[204:207], v[114:117], v[30:33]
	v_mfma_f32_16x16x32_bf16 v[86:89], v[196:199], v[122:125], v[86:89]
	v_mfma_f32_16x16x32_bf16 v[26:29], v[204:207], v[122:125], v[26:29]
	v_mfma_f32_16x16x32_bf16 v[82:85], v[196:199], v[138:141], v[82:85]
	v_mfma_f32_16x16x32_bf16 v[18:21], v[204:207], v[138:141], v[18:21]
	v_mfma_f32_16x16x32_bf16 v[90:93], v[196:199], v[184:187], v[90:93]
	v_mfma_f32_16x16x32_bf16 v[22:25], v[204:207], v[184:187], v[22:25]
	v_mfma_f32_16x16x32_bf16 v[94:97], v[200:203], v[118:121], v[94:97]
	v_mfma_f32_16x16x32_bf16 v[30:33], v[208:211], v[118:121], v[30:33]
	v_mfma_f32_16x16x32_bf16 v[86:89], v[200:203], v[126:129], v[86:89]
	v_mfma_f32_16x16x32_bf16 v[26:29], v[208:211], v[126:129], v[26:29]
	v_mfma_f32_16x16x32_bf16 v[82:85], v[200:203], v[162:165], v[82:85]
	v_mfma_f32_16x16x32_bf16 v[18:21], v[208:211], v[162:165], v[18:21]
	v_mfma_f32_16x16x32_bf16 v[90:93], v[200:203], v[188:191], v[90:93]
	v_mfma_f32_16x16x32_bf16 v[22:25], v[208:211], v[188:191], v[22:25]
	s_setprio 0
	s_add_i32 s17, s17, 2
	s_add_u32 s4, s4, 0x100
	s_addc_u32 s5, s5, 0
	s_add_u32 s15, s15, 0x100
	s_addc_u32 s16, s16, 0
	s_cmp_gt_u32 s17, 13
	s_barrier
	s_cbranch_scc0 .LBB0_455
	v_mbcnt_lo_u32_b32 v246, -1, 0
	v_mbcnt_hi_u32_b32 v246, -1, v246
	s_lshl_b32 s4, s12, 8
	s_add_i32 s5, s4, s67
	v_and_b32_e32 v247, 15, v246
	v_bfe_u32 v248, v246, 4, 2
	v_lshl_add_u32 v249, v247, 2, s67
	v_lshl_add_u32 v249, v249, 3, s98
	v_lshl_add_u32 v246, v248, 3, s70
	v_lshl_add_u32 v246, v246, 2, s98
	s_lshl_b32 s6, s36, 8
	s_or_b32 s6, s6, s70
	v_lshl_add_u32 v244, v248, 3, s6
	v_lshlrev_b32_e32 v244, 2, v244
	ds_read_b128 v[184:187], v249 offset:5120
	ds_read_b128 v[188:191], v249 offset:5136
	ds_read_b128 v[192:195], v249 offset:6144
	ds_read_b128 v[196:199], v249 offset:6160
	ds_read_b128 v[98:101], v246 offset:0
	ds_read_b128 v[102:105], v246 offset:1024
	ds_read_b128 v[106:109], v246 offset:2048
	ds_read_b128 v[110:113], v246 offset:3072
	ds_read_b128 v[114:117], v246 offset:4096
	ds_read_b128 v[118:121], v246 offset:512
	ds_read_b128 v[122:125], v246 offset:1536
	ds_read_b128 v[126:129], v246 offset:2560
	ds_read_b128 v[138:141], v246 offset:3584
	ds_read_b128 v[162:165], v246 offset:4608
	s_lshl_b32 s42, s12, 2
	s_add_i32 s42, s42, s66
	s_mul_i32 s16, s42, 0x16000
	s_mul_hi_u32 s17, s42, 0x16000
	s_add_u32 s54, s50, s16
	s_addc_u32 s55, s51, s17
	s_mul_i32 s16, s5, 0x1600
	s_mul_hi_u32 s17, s5, 0x1600
	s_add_u32 s74, s90, s16
	s_addc_u32 s75, s91, s17
	s_lshl_b32 s16, s36, 8
	s_lshl_b32 s17, s70, 1
	s_add_i32 s16, s16, s17
	s_add_u32 s74, s74, s16
	s_addc_u32 s75, s75, 0
	v_cmp_eq_u32_e64 s[4:5], 0, v247
	v_cmp_eq_u32_e64 s[6:7], 15, v247
	v_mul_u32_u24_e32 v245, 0x5800, v247
	v_lshl_add_u32 v245, v248, 4, v245
	v_mov_b32_e32 v240, 0xbfb8aa3b
	v_mov_b32_e32 v241, 0xbfb8aa3b
	s_waitcnt lgkmcnt(10)
	v_cvt_f32_u32_e32 v242, v185
	v_cvt_f32_u32_e32 v243, v184
	v_fmamk_f32 v242, v242, 0x4f800000, v243
	v_fmamk_f32 v242, v242, 0x30800000, v251
	v_rsq_f32_e32 v224, v242
	v_cvt_f32_u32_e32 v242, v187
	v_cvt_f32_u32_e32 v243, v186
	v_fmamk_f32 v242, v242, 0x4f800000, v243
	v_fmamk_f32 v242, v242, 0x30800000, v251
	v_rsq_f32_e32 v225, v242
	v_cvt_f32_u32_e32 v242, v189
	v_cvt_f32_u32_e32 v243, v188
	v_fmamk_f32 v242, v242, 0x4f800000, v243
	v_fmamk_f32 v242, v242, 0x30800000, v251
	v_rsq_f32_e32 v226, v242
	v_cvt_f32_u32_e32 v242, v191
	v_cvt_f32_u32_e32 v243, v190
	v_fmamk_f32 v242, v242, 0x4f800000, v243
	v_fmamk_f32 v242, v242, 0x30800000, v251
	v_rsq_f32_e32 v227, v242
	v_cvt_f32_u32_e32 v242, v193
	v_cvt_f32_u32_e32 v243, v192
	v_fmamk_f32 v242, v242, 0x4f800000, v243
	v_fmamk_f32 v242, v242, 0x30800000, v251
	v_rsq_f32_e32 v228, v242
	v_cvt_f32_u32_e32 v242, v195
	v_cvt_f32_u32_e32 v243, v194
	v_fmamk_f32 v242, v242, 0x4f800000, v243
	v_fmamk_f32 v242, v242, 0x30800000, v251
	v_rsq_f32_e32 v229, v242
	v_cvt_f32_u32_e32 v242, v197
	v_cvt_f32_u32_e32 v243, v196
	v_fmamk_f32 v242, v242, 0x4f800000, v243
	v_fmamk_f32 v242, v242, 0x30800000, v251
	v_rsq_f32_e32 v230, v242
	v_cvt_f32_u32_e32 v242, v199
	v_cvt_f32_u32_e32 v243, v198
	v_fmamk_f32 v242, v242, 0x4f800000, v243
	v_fmamk_f32 v242, v242, 0x30800000, v251
	v_rsq_f32_e32 v231, v242
	s_waitcnt lgkmcnt(0)
;     __device__ __forceinline__ void operator()(const f32x4 (&acc)[2][2][4][2], const Unit& u, int wr, int wc, int fr, int fq) const {
;     ...
;             for (int bj = 0; bj < 2; ++bj) { const int co = bj * HALF + 4 * n;
;                 prm[bj][0] = *(const f32x4*)(biasp + co); prm[bj][1] = *(const f32x4*)(cwp + co); prm[bj][2] = *(const f32x4*)(cwp + NUP + co); prm[bj][3] = *(const f32x4*)(cwp + 2 * NUP + co); prm[bj][4] = *(const f32x4*)(cwp + 3 * NUP + co); }
; #pragma unroll
;             for (int ai = 0; ai < 2; ++ai) {
;                 float* ep = edge + (size_t)(u.pm * 4 + ai * 2 + wr) * 4 * NUP + colt;
;                 f32x4 SG[4];
; #pragma unroll
;                 for (int bjr = 0; bjr < 2; ++bjr) { const int bj = 1 - bjr; const int co = bj * HALF + 4 * n;
;                     f32x4 U[4];
; #pragma unroll
;                     for (int m = 0; m < 4; ++m) U[m] = acc[ai][bj][m][n] * rs[ai][m] + prm[bj][0];
;                     if (fr < 2) *(f32x4*)(ep + (size_t)fr * NUP + co) = U[0];
;                     if (fr >= 14) *(f32x4*)(ep + (size_t)(fr - 12) * NUP + co) = U[3];
; #pragma unroll
;                     for (int m = 0; m < 4; ++m) { const f32x4 sp = (fr == 15 && m > 0) ? U[m > 0 ? m - 1 : 0] : U[m]; const f32x4 sn = (fr == 0 && m < 3) ? U[m < 3 ? m + 1 : 3] : U[m];
;                         f32x4 pv, nv;
; #pragma unroll
;                         for (int j = 0; j < 4; ++j) { pv[j] = __int_as_float(__builtin_amdgcn_update_dpp(0, __float_as_int(sp[j]), 0x121, 0xf, 0xf, false)); nv[j] = __int_as_float(__builtin_amdgcn_update_dpp(0, __float_as_int(sn[j]), 0x12F, 0xf, 0xf, false)); }
;                         const f32x4 R = prm[bj][1] * pv + prm[bj][2] * U[m] + prm[bj][3] * nv + prm[bj][4];
;                         if (bj == 1) {
; #pragma unroll
;                             for (int j = 0; j < 4; ++j) SG[m][j] = R[j] * __builtin_amdgcn_rcpf(1.0f + __expf(-R[j])); }
	ds_read_b128 v[184:187], v246 offset:16
	ds_read_b128 v[188:191], v246 offset:1040
	ds_read_b128 v[192:195], v246 offset:2064
	ds_read_b128 v[196:199], v246 offset:3088
	ds_read_b128 v[200:203], v246 offset:4112
	ds_read_b128 v[204:207], v246 offset:528
	ds_read_b128 v[208:211], v246 offset:1552
	ds_read_b128 v[212:215], v246 offset:2576
	ds_read_b128 v[216:219], v246 offset:3600
	ds_read_b128 v[220:223], v246 offset:4624
	v_pk_fma_f32 v[166:167], v[166:167], v[224:225], v[118:119] op_sel_hi:[1,0,1]
	v_pk_fma_f32 v[168:169], v[168:169], v[224:225], v[120:121] op_sel_hi:[1,0,1]
	v_pk_fma_f32 v[154:155], v[154:155], v[224:225], v[118:119] op_sel:[0,1,0] op_sel_hi:[1,1,1]
	v_pk_fma_f32 v[156:157], v[156:157], v[224:225], v[120:121] op_sel:[0,1,0] op_sel_hi:[1,1,1]
	v_pk_fma_f32 v[150:151], v[150:151], v[226:227], v[118:119] op_sel_hi:[1,0,1]
	v_pk_fma_f32 v[152:153], v[152:153], v[226:227], v[120:121] op_sel_hi:[1,0,1]
	v_pk_fma_f32 v[158:159], v[158:159], v[226:227], v[118:119] op_sel:[0,1,0] op_sel_hi:[1,1,1]
	v_pk_fma_f32 v[160:161], v[160:161], v[226:227], v[120:121] op_sel:[0,1,0] op_sel_hi:[1,1,1]
	s_mov_b64 exec, s[4:5]
	global_store_dwordx4 v244, v[166:169], s[54:55] offset:512
	s_add_u32 s16, s54, 0x5800
	s_addc_u32 s17, s55, 0
	global_store_dwordx4 v244, v[154:157], s[16:17] offset:512
	s_mov_b64 exec, s[6:7]
	s_add_u32 s56, s54, 0xb000
	s_addc_u32 s57, s55, 0
	global_store_dwordx4 v244, v[150:153], s[56:57] offset:512
	s_add_u32 s16, s54, 0x10800
	s_addc_u32 s17, s55, 0
	global_store_dwordx4 v244, v[158:161], s[16:17] offset:512
	s_mov_b64 exec, -1
	v_pk_fma_f32 v[232:233], v[126:127], v[166:167], v[162:163]
	v_pk_fma_f32 v[234:235], v[126:127], v[154:155], v[162:163]
	v_pk_fma_f32 v[236:237], v[126:127], v[150:151], v[162:163]
	v_pk_fma_f32 v[238:239], v[126:127], v[158:159], v[162:163]
	v_pk_fma_f32 v[234:235], v[122:123], v[166:167], v[234:235]
	v_pk_fma_f32 v[236:237], v[122:123], v[154:155], v[236:237]
	v_pk_fma_f32 v[238:239], v[122:123], v[150:151], v[238:239]
	v_pk_fma_f32 v[232:233], v[138:139], v[154:155], v[232:233]
	v_pk_fma_f32 v[234:235], v[138:139], v[150:151], v[234:235]
	v_pk_fma_f32 v[236:237], v[138:139], v[158:159], v[236:237]
	v_fmac_f32_dpp v232, v158, v122 row_ror:1 row_mask:0xf bank_mask:0xf
	v_fmac_f32_dpp v233, v159, v123 row_ror:1 row_mask:0xf bank_mask:0xf
	v_fmac_f32_dpp v238, v166, v138 row_ror:15 row_mask:0xf bank_mask:0xf
	v_fmac_f32_dpp v239, v167, v139 row_ror:15 row_mask:0xf bank_mask:0xf
	v_pk_mul_f32 v[166:167], v[232:233], v[240:241]
	v_pk_mul_f32 v[154:155], v[234:235], v[240:241]
	v_pk_mul_f32 v[150:151], v[236:237], v[240:241]
	v_pk_mul_f32 v[158:159], v[238:239], v[240:241]
	v_exp_f32_e32 v166, v166
	v_exp_f32_e32 v167, v167
	v_exp_f32_e32 v154, v154
	v_exp_f32_e32 v155, v155
	v_exp_f32_e32 v150, v150
	v_exp_f32_e32 v151, v151
	v_exp_f32_e32 v158, v158
	v_exp_f32_e32 v159, v159
	v_add_f32_e32 v166, 1.0, v166
	v_add_f32_e32 v167, 1.0, v167
	v_add_f32_e32 v154, 1.0, v154
	v_add_f32_e32 v155, 1.0, v155
	v_add_f32_e32 v150, 1.0, v150
	v_add_f32_e32 v151, 1.0, v151
	v_add_f32_e32 v158, 1.0, v158
	v_add_f32_e32 v159, 1.0, v159
	v_rcp_f32_e32 v166, v166
	v_rcp_f32_e32 v167, v167
	v_rcp_f32_e32 v154, v154
	v_rcp_f32_e32 v155, v155
	v_rcp_f32_e32 v150, v150
	v_rcp_f32_e32 v151, v151
	v_rcp_f32_e32 v158, v158
	v_rcp_f32_e32 v159, v159
	v_pk_mul_f32 v[166:167], v[232:233], v[166:167]
	v_pk_mul_f32 v[154:155], v[234:235], v[154:155]
	v_pk_mul_f32 v[150:151], v[236:237], v[150:151]
	v_pk_mul_f32 v[158:159], v[238:239], v[158:159]
	v_pk_fma_f32 v[232:233], v[128:129], v[168:169], v[164:165]
	v_pk_fma_f32 v[234:235], v[128:129], v[156:157], v[164:165]
	v_pk_fma_f32 v[236:237], v[128:129], v[152:153], v[164:165]
	v_pk_fma_f32 v[238:239], v[128:129], v[160:161], v[164:165]
	v_pk_fma_f32 v[234:235], v[124:125], v[168:169], v[234:235]
	v_pk_fma_f32 v[236:237], v[124:125], v[156:157], v[236:237]
	v_pk_fma_f32 v[238:239], v[124:125], v[152:153], v[238:239]
	v_pk_fma_f32 v[232:233], v[140:141], v[156:157], v[232:233]
	v_pk_fma_f32 v[234:235], v[140:141], v[152:153], v[234:235]
	v_pk_fma_f32 v[236:237], v[140:141], v[160:161], v[236:237]
	v_fmac_f32_dpp v232, v160, v124 row_ror:1 row_mask:0xf bank_mask:0xf
	v_fmac_f32_dpp v233, v161, v125 row_ror:1 row_mask:0xf bank_mask:0xf
	v_fmac_f32_dpp v238, v168, v140 row_ror:15 row_mask:0xf bank_mask:0xf
	v_fmac_f32_dpp v239, v169, v141 row_ror:15 row_mask:0xf bank_mask:0xf
	v_pk_mul_f32 v[168:169], v[232:233], v[240:241]
	v_pk_mul_f32 v[156:157], v[234:235], v[240:241]
	v_pk_mul_f32 v[152:153], v[236:237], v[240:241]
	v_pk_mul_f32 v[160:161], v[238:239], v[240:241]
	v_exp_f32_e32 v168, v168
	v_exp_f32_e32 v169, v169
	v_exp_f32_e32 v156, v156
	v_exp_f32_e32 v157, v157
	v_exp_f32_e32 v152, v152
	v_exp_f32_e32 v153, v153
	v_exp_f32_e32 v160, v160
	v_exp_f32_e32 v161, v161
	v_add_f32_e32 v168, 1.0, v168
	v_add_f32_e32 v169, 1.0, v169
	v_add_f32_e32 v156, 1.0, v156
	v_add_f32_e32 v157, 1.0, v157
	v_add_f32_e32 v152, 1.0, v152
	v_add_f32_e32 v153, 1.0, v153
	v_add_f32_e32 v160, 1.0, v160
	v_add_f32_e32 v161, 1.0, v161
	v_rcp_f32_e32 v168, v168
	v_rcp_f32_e32 v169, v169
	v_rcp_f32_e32 v156, v156
	v_rcp_f32_e32 v157, v157
	v_rcp_f32_e32 v152, v152
	v_rcp_f32_e32 v153, v153
	v_rcp_f32_e32 v160, v160
	v_rcp_f32_e32 v161, v161
	v_pk_mul_f32 v[168:169], v[232:233], v[168:169]
	v_pk_mul_f32 v[156:157], v[234:235], v[156:157]
	v_pk_mul_f32 v[152:153], v[236:237], v[152:153]
	v_pk_mul_f32 v[160:161], v[238:239], v[160:161]
	v_pk_fma_f32 v[146:147], v[146:147], v[224:225], v[98:99] op_sel_hi:[1,0,1]
	v_pk_fma_f32 v[148:149], v[148:149], v[224:225], v[100:101] op_sel_hi:[1,0,1]
; __device__ __forceinline__ unsigned cvt_pk_bf16_asm(float lo, float hi) { unsigned r; asm volatile("v_cvt_pk_bf16_f32 %0, %1, %2" : "=v"(r) : "v"(lo), "v"(hi)); return r; }
;     __device__ __forceinline__ void operator()(const f32x4 (&acc)[2][2][4][2], const Unit& u, int wr, int wc, int fr, int fq) const {
;     ...
;                 for (int bjr = 0; bjr < 2; ++bjr) { const int bj = 1 - bjr; const int co = bj * HALF + 4 * n;
;                     f32x4 U[4];
; #pragma unroll
;                     for (int m = 0; m < 4; ++m) U[m] = acc[ai][bj][m][n] * rs[ai][m] + prm[bj][0];
;                     if (fr < 2) *(f32x4*)(ep + (size_t)fr * NUP + co) = U[0];
;                     if (fr >= 14) *(f32x4*)(ep + (size_t)(fr - 12) * NUP + co) = U[3];
; #pragma unroll
;                     for (int m = 0; m < 4; ++m) { const f32x4 sp = (fr == 15 && m > 0) ? U[m > 0 ? m - 1 : 0] : U[m]; const f32x4 sn = (fr == 0 && m < 3) ? U[m < 3 ? m + 1 : 3] : U[m];
;                         f32x4 pv, nv;
; #pragma unroll
;                         for (int j = 0; j < 4; ++j) { pv[j] = __int_as_float(__builtin_amdgcn_update_dpp(0, __float_as_int(sp[j]), 0x121, 0xf, 0xf, false)); nv[j] = __int_as_float(__builtin_amdgcn_update_dpp(0, __float_as_int(sn[j]), 0x12F, 0xf, 0xf, false)); }
;                         const f32x4 R = prm[bj][1] * pv + prm[bj][2] * U[m] + prm[bj][3] * nv + prm[bj][4];
;                         if (bj == 1) {
; #pragma unroll
;                             for (int j = 0; j < 4; ++j) SG[m][j] = R[j] * __builtin_amdgcn_rcpf(1.0f + __expf(-R[j])); }
;                         else { const int r = row0 + ai * HALF + m * 16; const bool skip = (m == 0 && fr == 0) || (m == 3 && fr == 15);
;                             const f32x4 o = R * SG[m]; u32x2 w; w.x = cvt_pk_bf16_asm(o[0], o[1]); w.y = cvt_pk_bf16_asm(o[2], o[3]);
;                             if (!skip) *(u32x2*)(act + (size_t)r * FFD + u.pn * 128 + wc * 32 + 8 * fq + 4 * n) = w; } } } }
	v_pk_fma_f32 v[134:135], v[134:135], v[224:225], v[98:99] op_sel:[0,1,0] op_sel_hi:[1,1,1]
	v_pk_fma_f32 v[136:137], v[136:137], v[224:225], v[100:101] op_sel:[0,1,0] op_sel_hi:[1,1,1]
	v_pk_fma_f32 v[130:131], v[130:131], v[226:227], v[98:99] op_sel_hi:[1,0,1]
	v_pk_fma_f32 v[132:133], v[132:133], v[226:227], v[100:101] op_sel_hi:[1,0,1]
	v_pk_fma_f32 v[142:143], v[142:143], v[226:227], v[98:99] op_sel:[0,1,0] op_sel_hi:[1,1,1]
	v_pk_fma_f32 v[144:145], v[144:145], v[226:227], v[100:101] op_sel:[0,1,0] op_sel_hi:[1,1,1]
	s_mov_b64 exec, s[4:5]
	global_store_dwordx4 v244, v[146:149], s[54:55]
	s_add_u32 s16, s54, 0x5800
	s_addc_u32 s17, s55, 0
	global_store_dwordx4 v244, v[134:137], s[16:17]
	s_mov_b64 exec, s[6:7]
	s_add_u32 s56, s54, 0xb000
	s_addc_u32 s57, s55, 0
	global_store_dwordx4 v244, v[130:133], s[56:57]
	s_add_u32 s16, s54, 0x10800
	s_addc_u32 s17, s55, 0
	global_store_dwordx4 v244, v[142:145], s[16:17]
	s_mov_b64 exec, -1
	v_pk_fma_f32 v[232:233], v[106:107], v[146:147], v[114:115]
	v_pk_fma_f32 v[234:235], v[106:107], v[134:135], v[114:115]
	v_pk_fma_f32 v[236:237], v[106:107], v[130:131], v[114:115]
	v_pk_fma_f32 v[238:239], v[106:107], v[142:143], v[114:115]
	v_pk_fma_f32 v[234:235], v[102:103], v[146:147], v[234:235]
	v_pk_fma_f32 v[236:237], v[102:103], v[134:135], v[236:237]
	v_pk_fma_f32 v[238:239], v[102:103], v[130:131], v[238:239]
	v_pk_fma_f32 v[232:233], v[110:111], v[134:135], v[232:233]
	v_pk_fma_f32 v[234:235], v[110:111], v[130:131], v[234:235]
	v_pk_fma_f32 v[236:237], v[110:111], v[142:143], v[236:237]
	v_fmac_f32_dpp v232, v142, v102 row_ror:1 row_mask:0xf bank_mask:0xf
	v_fmac_f32_dpp v233, v143, v103 row_ror:1 row_mask:0xf bank_mask:0xf
	v_fmac_f32_dpp v238, v146, v110 row_ror:15 row_mask:0xf bank_mask:0xf
	v_fmac_f32_dpp v239, v147, v111 row_ror:15 row_mask:0xf bank_mask:0xf
	v_pk_mul_f32 v[232:233], v[232:233], v[166:167]
	v_pk_mul_f32 v[234:235], v[234:235], v[154:155]
	v_pk_mul_f32 v[236:237], v[236:237], v[150:151]
	v_pk_mul_f32 v[238:239], v[238:239], v[158:159]
	v_cvt_pk_bf16_f32 v146, v232, v233
	v_cvt_pk_bf16_f32 v134, v234, v235
	v_cvt_pk_bf16_f32 v130, v236, v237
	v_cvt_pk_bf16_f32 v142, v238, v239
	v_pk_fma_f32 v[232:233], v[108:109], v[148:149], v[116:117]
	v_pk_fma_f32 v[234:235], v[108:109], v[136:137], v[116:117]
	v_pk_fma_f32 v[236:237], v[108:109], v[132:133], v[116:117]
	v_pk_fma_f32 v[238:239], v[108:109], v[144:145], v[116:117]
	v_pk_fma_f32 v[234:235], v[104:105], v[148:149], v[234:235]
	v_pk_fma_f32 v[236:237], v[104:105], v[136:137], v[236:237]
	v_pk_fma_f32 v[238:239], v[104:105], v[132:133], v[238:239]
	v_pk_fma_f32 v[232:233], v[112:113], v[136:137], v[232:233]
	v_pk_fma_f32 v[234:235], v[112:113], v[132:133], v[234:235]
	v_pk_fma_f32 v[236:237], v[112:113], v[144:145], v[236:237]
	v_fmac_f32_dpp v232, v144, v104 row_ror:1 row_mask:0xf bank_mask:0xf
	v_fmac_f32_dpp v233, v145, v105 row_ror:1 row_mask:0xf bank_mask:0xf
	v_fmac_f32_dpp v238, v148, v112 row_ror:15 row_mask:0xf bank_mask:0xf
	v_fmac_f32_dpp v239, v149, v113 row_ror:15 row_mask:0xf bank_mask:0xf
	v_pk_mul_f32 v[232:233], v[232:233], v[168:169]
	v_pk_mul_f32 v[234:235], v[234:235], v[156:157]
	v_pk_mul_f32 v[236:237], v[236:237], v[152:153]
	v_pk_mul_f32 v[238:239], v[238:239], v[160:161]
	v_cvt_pk_bf16_f32 v147, v232, v233
	v_cvt_pk_bf16_f32 v135, v234, v235
	v_cvt_pk_bf16_f32 v131, v236, v237
	v_cvt_pk_bf16_f32 v143, v238, v239
	s_add_u32 s54, s54, 0x2c000
	s_addc_u32 s55, s55, 0
	v_pk_fma_f32 v[94:95], v[94:95], v[228:229], v[118:119] op_sel_hi:[1,0,1]
	v_pk_fma_f32 v[96:97], v[96:97], v[228:229], v[120:121] op_sel_hi:[1,0,1]
	v_pk_fma_f32 v[86:87], v[86:87], v[228:229], v[118:119] op_sel:[0,1,0] op_sel_hi:[1,1,1]
	v_pk_fma_f32 v[88:89], v[88:89], v[228:229], v[120:121] op_sel:[0,1,0] op_sel_hi:[1,1,1]
	v_pk_fma_f32 v[82:83], v[82:83], v[230:231], v[118:119] op_sel_hi:[1,0,1]
	v_pk_fma_f32 v[84:85], v[84:85], v[230:231], v[120:121] op_sel_hi:[1,0,1]
	v_pk_fma_f32 v[90:91], v[90:91], v[230:231], v[118:119] op_sel:[0,1,0] op_sel_hi:[1,1,1]
	v_pk_fma_f32 v[92:93], v[92:93], v[230:231], v[120:121] op_sel:[0,1,0] op_sel_hi:[1,1,1]
	s_mov_b64 exec, s[4:5]
	global_store_dwordx4 v244, v[94:97], s[54:55] offset:512
	s_add_u32 s16, s54, 0x5800
	s_addc_u32 s17, s55, 0
	global_store_dwordx4 v244, v[86:89], s[16:17] offset:512
	s_mov_b64 exec, s[6:7]
	s_add_u32 s56, s54, 0xb000
	s_addc_u32 s57, s55, 0
	global_store_dwordx4 v244, v[82:85], s[56:57] offset:512
	s_add_u32 s16, s54, 0x10800
	s_addc_u32 s17, s55, 0
	global_store_dwordx4 v244, v[90:93], s[16:17] offset:512
	s_mov_b64 exec, -1
	v_pk_fma_f32 v[232:233], v[126:127], v[94:95], v[162:163]
	v_pk_fma_f32 v[234:235], v[126:127], v[86:87], v[162:163]
	v_pk_fma_f32 v[236:237], v[126:127], v[82:83], v[162:163]
	v_pk_fma_f32 v[238:239], v[126:127], v[90:91], v[162:163]
	v_pk_fma_f32 v[234:235], v[122:123], v[94:95], v[234:235]
	v_pk_fma_f32 v[236:237], v[122:123], v[86:87], v[236:237]
	v_pk_fma_f32 v[238:239], v[122:123], v[82:83], v[238:239]
	v_pk_fma_f32 v[232:233], v[138:139], v[86:87], v[232:233]
	v_pk_fma_f32 v[234:235], v[138:139], v[82:83], v[234:235]
	v_pk_fma_f32 v[236:237], v[138:139], v[90:91], v[236:237]
	v_fmac_f32_dpp v232, v90, v122 row_ror:1 row_mask:0xf bank_mask:0xf
	v_fmac_f32_dpp v233, v91, v123 row_ror:1 row_mask:0xf bank_mask:0xf
	v_fmac_f32_dpp v238, v94, v138 row_ror:15 row_mask:0xf bank_mask:0xf
	v_fmac_f32_dpp v239, v95, v139 row_ror:15 row_mask:0xf bank_mask:0xf
	v_pk_mul_f32 v[94:95], v[232:233], v[240:241]
	v_pk_mul_f32 v[86:87], v[234:235], v[240:241]
	v_pk_mul_f32 v[82:83], v[236:237], v[240:241]
	v_pk_mul_f32 v[90:91], v[238:239], v[240:241]
; __device__ __forceinline__ unsigned cvt_pk_bf16_asm(float lo, float hi) { unsigned r; asm volatile("v_cvt_pk_bf16_f32 %0, %1, %2" : "=v"(r) : "v"(lo), "v"(hi)); return r; }
;     __device__ __forceinline__ void operator()(const f32x4 (&acc)[2][2][4][2], const Unit& u, int wr, int wc, int fr, int fq) const {
;     ...
;             for (int ai = 0; ai < 2; ++ai) {
;                 float* ep = edge + (size_t)(u.pm * 4 + ai * 2 + wr) * 4 * NUP + colt;
;                 f32x4 SG[4];
; #pragma unroll
;                 for (int bjr = 0; bjr < 2; ++bjr) { const int bj = 1 - bjr; const int co = bj * HALF + 4 * n;
;                     f32x4 U[4];
; #pragma unroll
;                     for (int m = 0; m < 4; ++m) U[m] = acc[ai][bj][m][n] * rs[ai][m] + prm[bj][0];
;                     if (fr < 2) *(f32x4*)(ep + (size_t)fr * NUP + co) = U[0];
;                     if (fr >= 14) *(f32x4*)(ep + (size_t)(fr - 12) * NUP + co) = U[3];
; #pragma unroll
;                     for (int m = 0; m < 4; ++m) { const f32x4 sp = (fr == 15 && m > 0) ? U[m > 0 ? m - 1 : 0] : U[m]; const f32x4 sn = (fr == 0 && m < 3) ? U[m < 3 ? m + 1 : 3] : U[m];
;                         f32x4 pv, nv;
; #pragma unroll
;                         for (int j = 0; j < 4; ++j) { pv[j] = __int_as_float(__builtin_amdgcn_update_dpp(0, __float_as_int(sp[j]), 0x121, 0xf, 0xf, false)); nv[j] = __int_as_float(__builtin_amdgcn_update_dpp(0, __float_as_int(sn[j]), 0x12F, 0xf, 0xf, false)); }
;                         const f32x4 R = prm[bj][1] * pv + prm[bj][2] * U[m] + prm[bj][3] * nv + prm[bj][4];
;                         if (bj == 1) {
; #pragma unroll
;                             for (int j = 0; j < 4; ++j) SG[m][j] = R[j] * __builtin_amdgcn_rcpf(1.0f + __expf(-R[j])); }
;                         else { const int r = row0 + ai * HALF + m * 16; const bool skip = (m == 0 && fr == 0) || (m == 3 && fr == 15);
;                             const f32x4 o = R * SG[m]; u32x2 w; w.x = cvt_pk_bf16_asm(o[0], o[1]); w.y = cvt_pk_bf16_asm(o[2], o[3]);
;                             if (!skip) *(u32x2*)(act + (size_t)r * FFD + u.pn * 128 + wc * 32 + 8 * fq + 4 * n) = w; } } } }
	v_exp_f32_e32 v94, v94
	v_exp_f32_e32 v95, v95
	v_exp_f32_e32 v86, v86
	v_exp_f32_e32 v87, v87
	v_exp_f32_e32 v82, v82
	v_exp_f32_e32 v83, v83
	v_exp_f32_e32 v90, v90
	v_exp_f32_e32 v91, v91
	v_add_f32_e32 v94, 1.0, v94
	v_add_f32_e32 v95, 1.0, v95
	v_add_f32_e32 v86, 1.0, v86
	v_add_f32_e32 v87, 1.0, v87
	v_add_f32_e32 v82, 1.0, v82
	v_add_f32_e32 v83, 1.0, v83
	v_add_f32_e32 v90, 1.0, v90
	v_add_f32_e32 v91, 1.0, v91
	v_rcp_f32_e32 v94, v94
	v_rcp_f32_e32 v95, v95
	v_rcp_f32_e32 v86, v86
	v_rcp_f32_e32 v87, v87
	v_rcp_f32_e32 v82, v82
	v_rcp_f32_e32 v83, v83
	v_rcp_f32_e32 v90, v90
	v_rcp_f32_e32 v91, v91
	v_pk_mul_f32 v[94:95], v[232:233], v[94:95]
	v_pk_mul_f32 v[86:87], v[234:235], v[86:87]
	v_pk_mul_f32 v[82:83], v[236:237], v[82:83]
	v_pk_mul_f32 v[90:91], v[238:239], v[90:91]
	v_pk_fma_f32 v[232:233], v[128:129], v[96:97], v[164:165]
	v_pk_fma_f32 v[234:235], v[128:129], v[88:89], v[164:165]
	v_pk_fma_f32 v[236:237], v[128:129], v[84:85], v[164:165]
	v_pk_fma_f32 v[238:239], v[128:129], v[92:93], v[164:165]
	v_pk_fma_f32 v[234:235], v[124:125], v[96:97], v[234:235]
	v_pk_fma_f32 v[236:237], v[124:125], v[88:89], v[236:237]
	v_pk_fma_f32 v[238:239], v[124:125], v[84:85], v[238:239]
	v_pk_fma_f32 v[232:233], v[140:141], v[88:89], v[232:233]
	v_pk_fma_f32 v[234:235], v[140:141], v[84:85], v[234:235]
	v_pk_fma_f32 v[236:237], v[140:141], v[92:93], v[236:237]
	v_fmac_f32_dpp v232, v92, v124 row_ror:1 row_mask:0xf bank_mask:0xf
	v_fmac_f32_dpp v233, v93, v125 row_ror:1 row_mask:0xf bank_mask:0xf
	v_fmac_f32_dpp v238, v96, v140 row_ror:15 row_mask:0xf bank_mask:0xf
	v_fmac_f32_dpp v239, v97, v141 row_ror:15 row_mask:0xf bank_mask:0xf
	v_pk_mul_f32 v[96:97], v[232:233], v[240:241]
	v_pk_mul_f32 v[88:89], v[234:235], v[240:241]
	v_pk_mul_f32 v[84:85], v[236:237], v[240:241]
	v_pk_mul_f32 v[92:93], v[238:239], v[240:241]
	v_exp_f32_e32 v96, v96
	v_exp_f32_e32 v97, v97
	v_exp_f32_e32 v88, v88
	v_exp_f32_e32 v89, v89
	v_exp_f32_e32 v84, v84
	v_exp_f32_e32 v85, v85
	v_exp_f32_e32 v92, v92
	v_exp_f32_e32 v93, v93
	v_add_f32_e32 v96, 1.0, v96
	v_add_f32_e32 v97, 1.0, v97
	v_add_f32_e32 v88, 1.0, v88
	v_add_f32_e32 v89, 1.0, v89
	v_add_f32_e32 v84, 1.0, v84
	v_add_f32_e32 v85, 1.0, v85
	v_add_f32_e32 v92, 1.0, v92
	v_add_f32_e32 v93, 1.0, v93
	v_rcp_f32_e32 v96, v96
	v_rcp_f32_e32 v97, v97
	v_rcp_f32_e32 v88, v88
	v_rcp_f32_e32 v89, v89
	v_rcp_f32_e32 v84, v84
	v_rcp_f32_e32 v85, v85
	v_rcp_f32_e32 v92, v92
	v_rcp_f32_e32 v93, v93
	v_pk_mul_f32 v[96:97], v[232:233], v[96:97]
	v_pk_mul_f32 v[88:89], v[234:235], v[88:89]
	v_pk_mul_f32 v[84:85], v[236:237], v[84:85]
	v_pk_mul_f32 v[92:93], v[238:239], v[92:93]
	v_pk_fma_f32 v[78:79], v[78:79], v[228:229], v[98:99] op_sel_hi:[1,0,1]
	v_pk_fma_f32 v[80:81], v[80:81], v[228:229], v[100:101] op_sel_hi:[1,0,1]
	v_pk_fma_f32 v[70:71], v[70:71], v[228:229], v[98:99] op_sel:[0,1,0] op_sel_hi:[1,1,1]
	v_pk_fma_f32 v[72:73], v[72:73], v[228:229], v[100:101] op_sel:[0,1,0] op_sel_hi:[1,1,1]
	v_pk_fma_f32 v[66:67], v[66:67], v[230:231], v[98:99] op_sel_hi:[1,0,1]
	v_pk_fma_f32 v[68:69], v[68:69], v[230:231], v[100:101] op_sel_hi:[1,0,1]
	v_pk_fma_f32 v[74:75], v[74:75], v[230:231], v[98:99] op_sel:[0,1,0] op_sel_hi:[1,1,1]
	v_pk_fma_f32 v[76:77], v[76:77], v[230:231], v[100:101] op_sel:[0,1,0] op_sel_hi:[1,1,1]
	s_mov_b64 exec, s[4:5]
	global_store_dwordx4 v244, v[78:81], s[54:55]
	s_add_u32 s16, s54, 0x5800
	s_addc_u32 s17, s55, 0
	global_store_dwordx4 v244, v[70:73], s[16:17]
	s_mov_b64 exec, s[6:7]
	s_add_u32 s56, s54, 0xb000
	s_addc_u32 s57, s55, 0
	global_store_dwordx4 v244, v[66:69], s[56:57]
	s_add_u32 s16, s54, 0x10800
	s_addc_u32 s17, s55, 0
	global_store_dwordx4 v244, v[74:77], s[16:17]
	s_mov_b64 exec, -1
	v_pk_fma_f32 v[232:233], v[106:107], v[78:79], v[114:115]
	v_pk_fma_f32 v[234:235], v[106:107], v[70:71], v[114:115]
	v_pk_fma_f32 v[236:237], v[106:107], v[66:67], v[114:115]
	v_pk_fma_f32 v[238:239], v[106:107], v[74:75], v[114:115]
	v_pk_fma_f32 v[234:235], v[102:103], v[78:79], v[234:235]
	v_pk_fma_f32 v[236:237], v[102:103], v[70:71], v[236:237]
	v_pk_fma_f32 v[238:239], v[102:103], v[66:67], v[238:239]
	v_pk_fma_f32 v[232:233], v[110:111], v[70:71], v[232:233]
	v_pk_fma_f32 v[234:235], v[110:111], v[66:67], v[234:235]
	v_pk_fma_f32 v[236:237], v[110:111], v[74:75], v[236:237]
	v_fmac_f32_dpp v232, v74, v102 row_ror:1 row_mask:0xf bank_mask:0xf
	v_fmac_f32_dpp v233, v75, v103 row_ror:1 row_mask:0xf bank_mask:0xf
	v_fmac_f32_dpp v238, v78, v110 row_ror:15 row_mask:0xf bank_mask:0xf
	v_fmac_f32_dpp v239, v79, v111 row_ror:15 row_mask:0xf bank_mask:0xf
	v_pk_mul_f32 v[232:233], v[232:233], v[94:95]
	v_pk_mul_f32 v[234:235], v[234:235], v[86:87]
	v_pk_mul_f32 v[236:237], v[236:237], v[82:83]
	v_pk_mul_f32 v[238:239], v[238:239], v[90:91]
	v_cvt_pk_bf16_f32 v78, v232, v233
	v_cvt_pk_bf16_f32 v70, v234, v235
	v_cvt_pk_bf16_f32 v66, v236, v237
	v_cvt_pk_bf16_f32 v74, v238, v239
	v_pk_fma_f32 v[232:233], v[108:109], v[80:81], v[116:117]
	v_pk_fma_f32 v[234:235], v[108:109], v[72:73], v[116:117]
	v_pk_fma_f32 v[236:237], v[108:109], v[68:69], v[116:117]
	v_pk_fma_f32 v[238:239], v[108:109], v[76:77], v[116:117]
	v_pk_fma_f32 v[234:235], v[104:105], v[80:81], v[234:235]
	v_pk_fma_f32 v[236:237], v[104:105], v[72:73], v[236:237]
	v_pk_fma_f32 v[238:239], v[104:105], v[68:69], v[238:239]
	v_pk_fma_f32 v[232:233], v[112:113], v[72:73], v[232:233]
	v_pk_fma_f32 v[234:235], v[112:113], v[68:69], v[234:235]
	v_pk_fma_f32 v[236:237], v[112:113], v[76:77], v[236:237]
	v_fmac_f32_dpp v232, v76, v104 row_ror:1 row_mask:0xf bank_mask:0xf
	v_fmac_f32_dpp v233, v77, v105 row_ror:1 row_mask:0xf bank_mask:0xf
	v_fmac_f32_dpp v238, v80, v112 row_ror:15 row_mask:0xf bank_mask:0xf
	v_fmac_f32_dpp v239, v81, v113 row_ror:15 row_mask:0xf bank_mask:0xf
	v_pk_mul_f32 v[232:233], v[232:233], v[96:97]
	v_pk_mul_f32 v[234:235], v[234:235], v[88:89]
	v_pk_mul_f32 v[236:237], v[236:237], v[84:85]
	v_pk_mul_f32 v[238:239], v[238:239], v[92:93]
	v_cvt_pk_bf16_f32 v79, v232, v233
	v_cvt_pk_bf16_f32 v71, v234, v235
	v_cvt_pk_bf16_f32 v67, v236, v237
	v_cvt_pk_bf16_f32 v75, v238, v239
	s_waitcnt lgkmcnt(0)
; __device__ __forceinline__ unsigned cvt_pk_bf16_asm(float lo, float hi) { unsigned r; asm volatile("v_cvt_pk_bf16_f32 %0, %1, %2" : "=v"(r) : "v"(lo), "v"(hi)); return r; }
;     __device__ __forceinline__ void operator()(const f32x4 (&acc)[2][2][4][2], const Unit& u, int wr, int wc, int fr, int fq) const {
;     ...
;             for (int ai = 0; ai < 2; ++ai) {
;                 float* ep = edge + (size_t)(u.pm * 4 + ai * 2 + wr) * 4 * NUP + colt;
;                 f32x4 SG[4];
; #pragma unroll
;                 for (int bjr = 0; bjr < 2; ++bjr) { const int bj = 1 - bjr; const int co = bj * HALF + 4 * n;
;                     f32x4 U[4];
; #pragma unroll
;                     for (int m = 0; m < 4; ++m) U[m] = acc[ai][bj][m][n] * rs[ai][m] + prm[bj][0];
;                     if (fr < 2) *(f32x4*)(ep + (size_t)fr * NUP + co) = U[0];
;                     if (fr >= 14) *(f32x4*)(ep + (size_t)(fr - 12) * NUP + co) = U[3];
; #pragma unroll
;                     for (int m = 0; m < 4; ++m) { const f32x4 sp = (fr == 15 && m > 0) ? U[m > 0 ? m - 1 : 0] : U[m]; const f32x4 sn = (fr == 0 && m < 3) ? U[m < 3 ? m + 1 : 3] : U[m];
;                         f32x4 pv, nv;
; #pragma unroll
;                         for (int j = 0; j < 4; ++j) { pv[j] = __int_as_float(__builtin_amdgcn_update_dpp(0, __float_as_int(sp[j]), 0x121, 0xf, 0xf, false)); nv[j] = __int_as_float(__builtin_amdgcn_update_dpp(0, __float_as_int(sn[j]), 0x12F, 0xf, 0xf, false)); }
;                         const f32x4 R = prm[bj][1] * pv + prm[bj][2] * U[m] + prm[bj][3] * nv + prm[bj][4];
;                         if (bj == 1) {
; #pragma unroll
;                             for (int j = 0; j < 4; ++j) SG[m][j] = R[j] * __builtin_amdgcn_rcpf(1.0f + __expf(-R[j])); }
;                         else { const int r = row0 + ai * HALF + m * 16; const bool skip = (m == 0 && fr == 0) || (m == 3 && fr == 15);
;                             const f32x4 o = R * SG[m]; u32x2 w; w.x = cvt_pk_bf16_asm(o[0], o[1]); w.y = cvt_pk_bf16_asm(o[2], o[3]);
;                             if (!skip) *(u32x2*)(act + (size_t)r * FFD + u.pn * 128 + wc * 32 + 8 * fq + 4 * n) = w; } } } }
	s_sub_u32 s54, s54, 0x2c000
	s_subb_u32 s55, s55, 0
	v_pk_fma_f32 v[62:63], v[62:63], v[224:225], v[204:205] op_sel_hi:[1,0,1]
	v_pk_fma_f32 v[64:65], v[64:65], v[224:225], v[206:207] op_sel_hi:[1,0,1]
	v_pk_fma_f32 v[54:55], v[54:55], v[224:225], v[204:205] op_sel:[0,1,0] op_sel_hi:[1,1,1]
	v_pk_fma_f32 v[56:57], v[56:57], v[224:225], v[206:207] op_sel:[0,1,0] op_sel_hi:[1,1,1]
	v_pk_fma_f32 v[50:51], v[50:51], v[226:227], v[204:205] op_sel_hi:[1,0,1]
	v_pk_fma_f32 v[52:53], v[52:53], v[226:227], v[206:207] op_sel_hi:[1,0,1]
	v_pk_fma_f32 v[58:59], v[58:59], v[226:227], v[204:205] op_sel:[0,1,0] op_sel_hi:[1,1,1]
	v_pk_fma_f32 v[60:61], v[60:61], v[226:227], v[206:207] op_sel:[0,1,0] op_sel_hi:[1,1,1]
	s_mov_b64 exec, s[4:5]
	global_store_dwordx4 v244, v[62:65], s[54:55] offset:528
	s_add_u32 s16, s54, 0x5800
	s_addc_u32 s17, s55, 0
	global_store_dwordx4 v244, v[54:57], s[16:17] offset:528
	s_mov_b64 exec, s[6:7]
	s_add_u32 s56, s54, 0xb000
	s_addc_u32 s57, s55, 0
	global_store_dwordx4 v244, v[50:53], s[56:57] offset:528
	s_add_u32 s16, s54, 0x10800
	s_addc_u32 s17, s55, 0
	global_store_dwordx4 v244, v[58:61], s[16:17] offset:528
	s_mov_b64 exec, -1
	v_pk_fma_f32 v[232:233], v[212:213], v[62:63], v[220:221]
	v_pk_fma_f32 v[234:235], v[212:213], v[54:55], v[220:221]
	v_pk_fma_f32 v[236:237], v[212:213], v[50:51], v[220:221]
	v_pk_fma_f32 v[238:239], v[212:213], v[58:59], v[220:221]
	v_pk_fma_f32 v[234:235], v[208:209], v[62:63], v[234:235]
	v_pk_fma_f32 v[236:237], v[208:209], v[54:55], v[236:237]
	v_pk_fma_f32 v[238:239], v[208:209], v[50:51], v[238:239]
	v_pk_fma_f32 v[232:233], v[216:217], v[54:55], v[232:233]
	v_pk_fma_f32 v[234:235], v[216:217], v[50:51], v[234:235]
	v_pk_fma_f32 v[236:237], v[216:217], v[58:59], v[236:237]
	v_fmac_f32_dpp v232, v58, v208 row_ror:1 row_mask:0xf bank_mask:0xf
	v_fmac_f32_dpp v233, v59, v209 row_ror:1 row_mask:0xf bank_mask:0xf
	v_fmac_f32_dpp v238, v62, v216 row_ror:15 row_mask:0xf bank_mask:0xf
	v_fmac_f32_dpp v239, v63, v217 row_ror:15 row_mask:0xf bank_mask:0xf
	v_pk_mul_f32 v[62:63], v[232:233], v[240:241]
	v_pk_mul_f32 v[54:55], v[234:235], v[240:241]
	v_pk_mul_f32 v[50:51], v[236:237], v[240:241]
	v_pk_mul_f32 v[58:59], v[238:239], v[240:241]
	v_exp_f32_e32 v62, v62
	v_exp_f32_e32 v63, v63
	v_exp_f32_e32 v54, v54
	v_exp_f32_e32 v55, v55
	v_exp_f32_e32 v50, v50
	v_exp_f32_e32 v51, v51
	v_exp_f32_e32 v58, v58
	v_exp_f32_e32 v59, v59
	v_add_f32_e32 v62, 1.0, v62
	v_add_f32_e32 v63, 1.0, v63
	v_add_f32_e32 v54, 1.0, v54
	v_add_f32_e32 v55, 1.0, v55
	v_add_f32_e32 v50, 1.0, v50
	v_add_f32_e32 v51, 1.0, v51
	v_add_f32_e32 v58, 1.0, v58
	v_add_f32_e32 v59, 1.0, v59
	v_rcp_f32_e32 v62, v62
	v_rcp_f32_e32 v63, v63
	v_rcp_f32_e32 v54, v54
	v_rcp_f32_e32 v55, v55
	v_rcp_f32_e32 v50, v50
	v_rcp_f32_e32 v51, v51
	v_rcp_f32_e32 v58, v58
	v_rcp_f32_e32 v59, v59
	v_pk_mul_f32 v[62:63], v[232:233], v[62:63]
	v_pk_mul_f32 v[54:55], v[234:235], v[54:55]
	v_pk_mul_f32 v[50:51], v[236:237], v[50:51]
	v_pk_mul_f32 v[58:59], v[238:239], v[58:59]
	v_pk_fma_f32 v[232:233], v[214:215], v[64:65], v[222:223]
	v_pk_fma_f32 v[234:235], v[214:215], v[56:57], v[222:223]
	v_pk_fma_f32 v[236:237], v[214:215], v[52:53], v[222:223]
	v_pk_fma_f32 v[238:239], v[214:215], v[60:61], v[222:223]
	v_pk_fma_f32 v[234:235], v[210:211], v[64:65], v[234:235]
	v_pk_fma_f32 v[236:237], v[210:211], v[56:57], v[236:237]
	v_pk_fma_f32 v[238:239], v[210:211], v[52:53], v[238:239]
	v_pk_fma_f32 v[232:233], v[218:219], v[56:57], v[232:233]
	v_pk_fma_f32 v[234:235], v[218:219], v[52:53], v[234:235]
	v_pk_fma_f32 v[236:237], v[218:219], v[60:61], v[236:237]
	v_fmac_f32_dpp v232, v60, v210 row_ror:1 row_mask:0xf bank_mask:0xf
	v_fmac_f32_dpp v233, v61, v211 row_ror:1 row_mask:0xf bank_mask:0xf
	v_fmac_f32_dpp v238, v64, v218 row_ror:15 row_mask:0xf bank_mask:0xf
	v_fmac_f32_dpp v239, v65, v219 row_ror:15 row_mask:0xf bank_mask:0xf
	v_pk_mul_f32 v[64:65], v[232:233], v[240:241]
	v_pk_mul_f32 v[56:57], v[234:235], v[240:241]
	v_pk_mul_f32 v[52:53], v[236:237], v[240:241]
	v_pk_mul_f32 v[60:61], v[238:239], v[240:241]
	v_exp_f32_e32 v64, v64
	v_exp_f32_e32 v65, v65
	v_exp_f32_e32 v56, v56
	v_exp_f32_e32 v57, v57
	v_exp_f32_e32 v52, v52
	v_exp_f32_e32 v53, v53
	v_exp_f32_e32 v60, v60
	v_exp_f32_e32 v61, v61
	v_add_f32_e32 v64, 1.0, v64
	v_add_f32_e32 v65, 1.0, v65
	v_add_f32_e32 v56, 1.0, v56
	v_add_f32_e32 v57, 1.0, v57
	v_add_f32_e32 v52, 1.0, v52
	v_add_f32_e32 v53, 1.0, v53
	v_add_f32_e32 v60, 1.0, v60
	v_add_f32_e32 v61, 1.0, v61
	v_rcp_f32_e32 v64, v64
	v_rcp_f32_e32 v65, v65
	v_rcp_f32_e32 v56, v56
	v_rcp_f32_e32 v57, v57
	v_rcp_f32_e32 v52, v52
	v_rcp_f32_e32 v53, v53
	v_rcp_f32_e32 v60, v60
	v_rcp_f32_e32 v61, v61
	v_pk_mul_f32 v[64:65], v[232:233], v[64:65]
	v_pk_mul_f32 v[56:57], v[234:235], v[56:57]
	v_pk_mul_f32 v[52:53], v[236:237], v[52:53]
	v_pk_mul_f32 v[60:61], v[238:239], v[60:61]
	v_pk_fma_f32 v[46:47], v[46:47], v[224:225], v[184:185] op_sel_hi:[1,0,1]
	v_pk_fma_f32 v[48:49], v[48:49], v[224:225], v[186:187] op_sel_hi:[1,0,1]
	v_pk_fma_f32 v[38:39], v[38:39], v[224:225], v[184:185] op_sel:[0,1,0] op_sel_hi:[1,1,1]
	v_pk_fma_f32 v[40:41], v[40:41], v[224:225], v[186:187] op_sel:[0,1,0] op_sel_hi:[1,1,1]
	v_pk_fma_f32 v[34:35], v[34:35], v[226:227], v[184:185] op_sel_hi:[1,0,1]
	v_pk_fma_f32 v[36:37], v[36:37], v[226:227], v[186:187] op_sel_hi:[1,0,1]
	v_pk_fma_f32 v[42:43], v[42:43], v[226:227], v[184:185] op_sel:[0,1,0] op_sel_hi:[1,1,1]
	v_pk_fma_f32 v[44:45], v[44:45], v[226:227], v[186:187] op_sel:[0,1,0] op_sel_hi:[1,1,1]
	s_mov_b64 exec, s[4:5]
	global_store_dwordx4 v244, v[46:49], s[54:55] offset:16
	s_add_u32 s16, s54, 0x5800
; __device__ __forceinline__ unsigned cvt_pk_bf16_asm(float lo, float hi) { unsigned r; asm volatile("v_cvt_pk_bf16_f32 %0, %1, %2" : "=v"(r) : "v"(lo), "v"(hi)); return r; }
;     __device__ __forceinline__ void operator()(const f32x4 (&acc)[2][2][4][2], const Unit& u, int wr, int wc, int fr, int fq) const {
;     ...
;                 for (int bjr = 0; bjr < 2; ++bjr) { const int bj = 1 - bjr; const int co = bj * HALF + 4 * n;
;                     f32x4 U[4];
; #pragma unroll
;                     for (int m = 0; m < 4; ++m) U[m] = acc[ai][bj][m][n] * rs[ai][m] + prm[bj][0];
;                     if (fr < 2) *(f32x4*)(ep + (size_t)fr * NUP + co) = U[0];
;                     if (fr >= 14) *(f32x4*)(ep + (size_t)(fr - 12) * NUP + co) = U[3];
; #pragma unroll
;                     for (int m = 0; m < 4; ++m) { const f32x4 sp = (fr == 15 && m > 0) ? U[m > 0 ? m - 1 : 0] : U[m]; const f32x4 sn = (fr == 0 && m < 3) ? U[m < 3 ? m + 1 : 3] : U[m];
;                         f32x4 pv, nv;
; #pragma unroll
;                         for (int j = 0; j < 4; ++j) { pv[j] = __int_as_float(__builtin_amdgcn_update_dpp(0, __float_as_int(sp[j]), 0x121, 0xf, 0xf, false)); nv[j] = __int_as_float(__builtin_amdgcn_update_dpp(0, __float_as_int(sn[j]), 0x12F, 0xf, 0xf, false)); }
;                         const f32x4 R = prm[bj][1] * pv + prm[bj][2] * U[m] + prm[bj][3] * nv + prm[bj][4];
;                         if (bj == 1) {
; #pragma unroll
;                             for (int j = 0; j < 4; ++j) SG[m][j] = R[j] * __builtin_amdgcn_rcpf(1.0f + __expf(-R[j])); }
;                         else { const int r = row0 + ai * HALF + m * 16; const bool skip = (m == 0 && fr == 0) || (m == 3 && fr == 15);
;                             const f32x4 o = R * SG[m]; u32x2 w; w.x = cvt_pk_bf16_asm(o[0], o[1]); w.y = cvt_pk_bf16_asm(o[2], o[3]);
;                             if (!skip) *(u32x2*)(act + (size_t)r * FFD + u.pn * 128 + wc * 32 + 8 * fq + 4 * n) = w; } } } }
	s_addc_u32 s17, s55, 0
	global_store_dwordx4 v244, v[38:41], s[16:17] offset:16
	s_mov_b64 exec, s[6:7]
	s_add_u32 s56, s54, 0xb000
	s_addc_u32 s57, s55, 0
	global_store_dwordx4 v244, v[34:37], s[56:57] offset:16
	s_add_u32 s16, s54, 0x10800
	s_addc_u32 s17, s55, 0
	global_store_dwordx4 v244, v[42:45], s[16:17] offset:16
	s_mov_b64 exec, -1
	v_pk_fma_f32 v[232:233], v[192:193], v[46:47], v[200:201]
	v_pk_fma_f32 v[234:235], v[192:193], v[38:39], v[200:201]
	v_pk_fma_f32 v[236:237], v[192:193], v[34:35], v[200:201]
	v_pk_fma_f32 v[238:239], v[192:193], v[42:43], v[200:201]
	v_pk_fma_f32 v[234:235], v[188:189], v[46:47], v[234:235]
	v_pk_fma_f32 v[236:237], v[188:189], v[38:39], v[236:237]
	v_pk_fma_f32 v[238:239], v[188:189], v[34:35], v[238:239]
	v_pk_fma_f32 v[232:233], v[196:197], v[38:39], v[232:233]
	v_pk_fma_f32 v[234:235], v[196:197], v[34:35], v[234:235]
	v_pk_fma_f32 v[236:237], v[196:197], v[42:43], v[236:237]
	v_fmac_f32_dpp v232, v42, v188 row_ror:1 row_mask:0xf bank_mask:0xf
	v_fmac_f32_dpp v233, v43, v189 row_ror:1 row_mask:0xf bank_mask:0xf
	v_fmac_f32_dpp v238, v46, v196 row_ror:15 row_mask:0xf bank_mask:0xf
	v_fmac_f32_dpp v239, v47, v197 row_ror:15 row_mask:0xf bank_mask:0xf
	v_pk_mul_f32 v[232:233], v[232:233], v[62:63]
	v_pk_mul_f32 v[234:235], v[234:235], v[54:55]
	v_pk_mul_f32 v[236:237], v[236:237], v[50:51]
	v_pk_mul_f32 v[238:239], v[238:239], v[58:59]
	v_cvt_pk_bf16_f32 v148, v232, v233
	v_cvt_pk_bf16_f32 v136, v234, v235
	v_cvt_pk_bf16_f32 v132, v236, v237
	v_cvt_pk_bf16_f32 v144, v238, v239
	v_pk_fma_f32 v[232:233], v[194:195], v[48:49], v[202:203]
	v_pk_fma_f32 v[234:235], v[194:195], v[40:41], v[202:203]
	v_pk_fma_f32 v[236:237], v[194:195], v[36:37], v[202:203]
	v_pk_fma_f32 v[238:239], v[194:195], v[44:45], v[202:203]
	v_pk_fma_f32 v[234:235], v[190:191], v[48:49], v[234:235]
	v_pk_fma_f32 v[236:237], v[190:191], v[40:41], v[236:237]
	v_pk_fma_f32 v[238:239], v[190:191], v[36:37], v[238:239]
	v_pk_fma_f32 v[232:233], v[198:199], v[40:41], v[232:233]
	v_pk_fma_f32 v[234:235], v[198:199], v[36:37], v[234:235]
	v_pk_fma_f32 v[236:237], v[198:199], v[44:45], v[236:237]
	v_fmac_f32_dpp v232, v44, v190 row_ror:1 row_mask:0xf bank_mask:0xf
	v_fmac_f32_dpp v233, v45, v191 row_ror:1 row_mask:0xf bank_mask:0xf
	v_fmac_f32_dpp v238, v48, v198 row_ror:15 row_mask:0xf bank_mask:0xf
	v_fmac_f32_dpp v239, v49, v199 row_ror:15 row_mask:0xf bank_mask:0xf
	v_pk_mul_f32 v[232:233], v[232:233], v[64:65]
	v_pk_mul_f32 v[234:235], v[234:235], v[56:57]
	v_pk_mul_f32 v[236:237], v[236:237], v[52:53]
	v_pk_mul_f32 v[238:239], v[238:239], v[60:61]
	v_cvt_pk_bf16_f32 v149, v232, v233
	v_cvt_pk_bf16_f32 v137, v234, v235
	v_cvt_pk_bf16_f32 v133, v236, v237
	v_cvt_pk_bf16_f32 v145, v238, v239
	s_add_u32 s16, s74, 0x0
	s_addc_u32 s17, s75, 0
	s_not_b64 exec, s[4:5]
	global_store_dwordx4 v245, v[146:149], s[16:17]
	s_mov_b64 exec, -1
	s_add_u32 s16, s74, 0x1600
	s_addc_u32 s17, s75, 0
	global_store_dwordx4 v245, v[134:137], s[16:17]
	s_add_u32 s16, s74, 0x2c00
	s_addc_u32 s17, s75, 0
	global_store_dwordx4 v245, v[130:133], s[16:17]
	s_add_u32 s16, s74, 0x4200
	s_addc_u32 s17, s75, 0
	s_not_b64 exec, s[6:7]
	global_store_dwordx4 v245, v[142:145], s[16:17]
	s_mov_b64 exec, -1
	s_add_u32 s54, s54, 0x2c000
	s_addc_u32 s55, s55, 0
	v_pk_fma_f32 v[30:31], v[30:31], v[228:229], v[204:205] op_sel_hi:[1,0,1]
	v_pk_fma_f32 v[32:33], v[32:33], v[228:229], v[206:207] op_sel_hi:[1,0,1]
	v_pk_fma_f32 v[26:27], v[26:27], v[228:229], v[204:205] op_sel:[0,1,0] op_sel_hi:[1,1,1]
	v_pk_fma_f32 v[28:29], v[28:29], v[228:229], v[206:207] op_sel:[0,1,0] op_sel_hi:[1,1,1]
	v_pk_fma_f32 v[18:19], v[18:19], v[230:231], v[204:205] op_sel_hi:[1,0,1]
	v_pk_fma_f32 v[20:21], v[20:21], v[230:231], v[206:207] op_sel_hi:[1,0,1]
	v_pk_fma_f32 v[22:23], v[22:23], v[230:231], v[204:205] op_sel:[0,1,0] op_sel_hi:[1,1,1]
	v_pk_fma_f32 v[24:25], v[24:25], v[230:231], v[206:207] op_sel:[0,1,0] op_sel_hi:[1,1,1]
	s_mov_b64 exec, s[4:5]
	global_store_dwordx4 v244, v[30:33], s[54:55] offset:528
	s_add_u32 s16, s54, 0x5800
	s_addc_u32 s17, s55, 0
	global_store_dwordx4 v244, v[26:29], s[16:17] offset:528
	s_mov_b64 exec, s[6:7]
	s_add_u32 s56, s54, 0xb000
	s_addc_u32 s57, s55, 0
	global_store_dwordx4 v244, v[18:21], s[56:57] offset:528
	s_add_u32 s16, s54, 0x10800
	s_addc_u32 s17, s55, 0
	global_store_dwordx4 v244, v[22:25], s[16:17] offset:528
	s_mov_b64 exec, -1
	v_pk_fma_f32 v[232:233], v[212:213], v[30:31], v[220:221]
	v_pk_fma_f32 v[234:235], v[212:213], v[26:27], v[220:221]
	v_pk_fma_f32 v[236:237], v[212:213], v[18:19], v[220:221]
	v_pk_fma_f32 v[238:239], v[212:213], v[22:23], v[220:221]
	v_pk_fma_f32 v[234:235], v[208:209], v[30:31], v[234:235]
	v_pk_fma_f32 v[236:237], v[208:209], v[26:27], v[236:237]
	v_pk_fma_f32 v[238:239], v[208:209], v[18:19], v[238:239]
	v_pk_fma_f32 v[232:233], v[216:217], v[26:27], v[232:233]
	v_pk_fma_f32 v[234:235], v[216:217], v[18:19], v[234:235]
	v_pk_fma_f32 v[236:237], v[216:217], v[22:23], v[236:237]
	v_fmac_f32_dpp v232, v22, v208 row_ror:1 row_mask:0xf bank_mask:0xf
	v_fmac_f32_dpp v233, v23, v209 row_ror:1 row_mask:0xf bank_mask:0xf
	v_fmac_f32_dpp v238, v30, v216 row_ror:15 row_mask:0xf bank_mask:0xf
	v_fmac_f32_dpp v239, v31, v217 row_ror:15 row_mask:0xf bank_mask:0xf
	v_pk_mul_f32 v[30:31], v[232:233], v[240:241]
	v_pk_mul_f32 v[26:27], v[234:235], v[240:241]
	v_pk_mul_f32 v[18:19], v[236:237], v[240:241]
	v_pk_mul_f32 v[22:23], v[238:239], v[240:241]
	v_exp_f32_e32 v30, v30
	v_exp_f32_e32 v31, v31
	v_exp_f32_e32 v26, v26
	v_exp_f32_e32 v27, v27
	v_exp_f32_e32 v18, v18
	v_exp_f32_e32 v19, v19
	v_exp_f32_e32 v22, v22
	v_exp_f32_e32 v23, v23
; __device__ __forceinline__ unsigned cvt_pk_bf16_asm(float lo, float hi) { unsigned r; asm volatile("v_cvt_pk_bf16_f32 %0, %1, %2" : "=v"(r) : "v"(lo), "v"(hi)); return r; }
;     __device__ __forceinline__ void operator()(const f32x4 (&acc)[2][2][4][2], const Unit& u, int wr, int wc, int fr, int fq) const {
;     ...
;                 for (int bjr = 0; bjr < 2; ++bjr) { const int bj = 1 - bjr; const int co = bj * HALF + 4 * n;
;                     f32x4 U[4];
; #pragma unroll
;                     for (int m = 0; m < 4; ++m) U[m] = acc[ai][bj][m][n] * rs[ai][m] + prm[bj][0];
;                     if (fr < 2) *(f32x4*)(ep + (size_t)fr * NUP + co) = U[0];
;                     if (fr >= 14) *(f32x4*)(ep + (size_t)(fr - 12) * NUP + co) = U[3];
; #pragma unroll
;                     for (int m = 0; m < 4; ++m) { const f32x4 sp = (fr == 15 && m > 0) ? U[m > 0 ? m - 1 : 0] : U[m]; const f32x4 sn = (fr == 0 && m < 3) ? U[m < 3 ? m + 1 : 3] : U[m];
;                         f32x4 pv, nv;
; #pragma unroll
;                         for (int j = 0; j < 4; ++j) { pv[j] = __int_as_float(__builtin_amdgcn_update_dpp(0, __float_as_int(sp[j]), 0x121, 0xf, 0xf, false)); nv[j] = __int_as_float(__builtin_amdgcn_update_dpp(0, __float_as_int(sn[j]), 0x12F, 0xf, 0xf, false)); }
;                         const f32x4 R = prm[bj][1] * pv + prm[bj][2] * U[m] + prm[bj][3] * nv + prm[bj][4];
;                         if (bj == 1) {
; #pragma unroll
;                             for (int j = 0; j < 4; ++j) SG[m][j] = R[j] * __builtin_amdgcn_rcpf(1.0f + __expf(-R[j])); }
;                         else { const int r = row0 + ai * HALF + m * 16; const bool skip = (m == 0 && fr == 0) || (m == 3 && fr == 15);
;                             const f32x4 o = R * SG[m]; u32x2 w; w.x = cvt_pk_bf16_asm(o[0], o[1]); w.y = cvt_pk_bf16_asm(o[2], o[3]);
;                             if (!skip) *(u32x2*)(act + (size_t)r * FFD + u.pn * 128 + wc * 32 + 8 * fq + 4 * n) = w; } } } }
	v_add_f32_e32 v30, 1.0, v30
	v_add_f32_e32 v31, 1.0, v31
	v_add_f32_e32 v26, 1.0, v26
	v_add_f32_e32 v27, 1.0, v27
	v_add_f32_e32 v18, 1.0, v18
	v_add_f32_e32 v19, 1.0, v19
	v_add_f32_e32 v22, 1.0, v22
	v_add_f32_e32 v23, 1.0, v23
	v_rcp_f32_e32 v30, v30
	v_rcp_f32_e32 v31, v31
	v_rcp_f32_e32 v26, v26
	v_rcp_f32_e32 v27, v27
	v_rcp_f32_e32 v18, v18
	v_rcp_f32_e32 v19, v19
	v_rcp_f32_e32 v22, v22
	v_rcp_f32_e32 v23, v23
	v_pk_mul_f32 v[30:31], v[232:233], v[30:31]
	v_pk_mul_f32 v[26:27], v[234:235], v[26:27]
	v_pk_mul_f32 v[18:19], v[236:237], v[18:19]
	v_pk_mul_f32 v[22:23], v[238:239], v[22:23]
	v_pk_fma_f32 v[232:233], v[214:215], v[32:33], v[222:223]
	v_pk_fma_f32 v[234:235], v[214:215], v[28:29], v[222:223]
	v_pk_fma_f32 v[236:237], v[214:215], v[20:21], v[222:223]
	v_pk_fma_f32 v[238:239], v[214:215], v[24:25], v[222:223]
	v_pk_fma_f32 v[234:235], v[210:211], v[32:33], v[234:235]
	v_pk_fma_f32 v[236:237], v[210:211], v[28:29], v[236:237]
	v_pk_fma_f32 v[238:239], v[210:211], v[20:21], v[238:239]
	v_pk_fma_f32 v[232:233], v[218:219], v[28:29], v[232:233]
	v_pk_fma_f32 v[234:235], v[218:219], v[20:21], v[234:235]
	v_pk_fma_f32 v[236:237], v[218:219], v[24:25], v[236:237]
	v_fmac_f32_dpp v232, v24, v210 row_ror:1 row_mask:0xf bank_mask:0xf
	v_fmac_f32_dpp v233, v25, v211 row_ror:1 row_mask:0xf bank_mask:0xf
	v_fmac_f32_dpp v238, v32, v218 row_ror:15 row_mask:0xf bank_mask:0xf
	v_fmac_f32_dpp v239, v33, v219 row_ror:15 row_mask:0xf bank_mask:0xf
	v_pk_mul_f32 v[32:33], v[232:233], v[240:241]
	v_pk_mul_f32 v[28:29], v[234:235], v[240:241]
	v_pk_mul_f32 v[20:21], v[236:237], v[240:241]
	v_pk_mul_f32 v[24:25], v[238:239], v[240:241]
	v_exp_f32_e32 v32, v32
	v_exp_f32_e32 v33, v33
	v_exp_f32_e32 v28, v28
	v_exp_f32_e32 v29, v29
	v_exp_f32_e32 v20, v20
	v_exp_f32_e32 v21, v21
	v_exp_f32_e32 v24, v24
	v_exp_f32_e32 v25, v25
	v_add_f32_e32 v32, 1.0, v32
	v_add_f32_e32 v33, 1.0, v33
	v_add_f32_e32 v28, 1.0, v28
	v_add_f32_e32 v29, 1.0, v29
	v_add_f32_e32 v20, 1.0, v20
	v_add_f32_e32 v21, 1.0, v21
	v_add_f32_e32 v24, 1.0, v24
	v_add_f32_e32 v25, 1.0, v25
	v_rcp_f32_e32 v32, v32
	v_rcp_f32_e32 v33, v33
	v_rcp_f32_e32 v28, v28
	v_rcp_f32_e32 v29, v29
	v_rcp_f32_e32 v20, v20
	v_rcp_f32_e32 v21, v21
	v_rcp_f32_e32 v24, v24
	v_rcp_f32_e32 v25, v25
	v_pk_mul_f32 v[32:33], v[232:233], v[32:33]
	v_pk_mul_f32 v[28:29], v[234:235], v[28:29]
	v_pk_mul_f32 v[20:21], v[236:237], v[20:21]
	v_pk_mul_f32 v[24:25], v[238:239], v[24:25]
	v_pk_fma_f32 v[14:15], v[14:15], v[228:229], v[184:185] op_sel_hi:[1,0,1]
	v_pk_fma_f32 v[16:17], v[16:17], v[228:229], v[186:187] op_sel_hi:[1,0,1]
	v_pk_fma_f32 v[6:7], v[6:7], v[228:229], v[184:185] op_sel:[0,1,0] op_sel_hi:[1,1,1]
	v_pk_fma_f32 v[8:9], v[8:9], v[228:229], v[186:187] op_sel:[0,1,0] op_sel_hi:[1,1,1]
	v_pk_fma_f32 v[2:3], v[2:3], v[230:231], v[184:185] op_sel_hi:[1,0,1]
	v_pk_fma_f32 v[4:5], v[4:5], v[230:231], v[186:187] op_sel_hi:[1,0,1]
	v_pk_fma_f32 v[10:11], v[10:11], v[230:231], v[184:185] op_sel:[0,1,0] op_sel_hi:[1,1,1]
	v_pk_fma_f32 v[12:13], v[12:13], v[230:231], v[186:187] op_sel:[0,1,0] op_sel_hi:[1,1,1]
	s_mov_b64 exec, s[4:5]
	global_store_dwordx4 v244, v[14:17], s[54:55] offset:16
	s_add_u32 s16, s54, 0x5800
	s_addc_u32 s17, s55, 0
	global_store_dwordx4 v244, v[6:9], s[16:17] offset:16
	s_mov_b64 exec, s[6:7]
	s_add_u32 s56, s54, 0xb000
	s_addc_u32 s57, s55, 0
	global_store_dwordx4 v244, v[2:5], s[56:57] offset:16
	s_add_u32 s16, s54, 0x10800
	s_addc_u32 s17, s55, 0
	global_store_dwordx4 v244, v[10:13], s[16:17] offset:16
	s_mov_b64 exec, -1
	v_pk_fma_f32 v[232:233], v[192:193], v[14:15], v[200:201]
	v_pk_fma_f32 v[234:235], v[192:193], v[6:7], v[200:201]
	v_pk_fma_f32 v[236:237], v[192:193], v[2:3], v[200:201]
	v_pk_fma_f32 v[238:239], v[192:193], v[10:11], v[200:201]
	v_pk_fma_f32 v[234:235], v[188:189], v[14:15], v[234:235]
	v_pk_fma_f32 v[236:237], v[188:189], v[6:7], v[236:237]
	v_pk_fma_f32 v[238:239], v[188:189], v[2:3], v[238:239]
	v_pk_fma_f32 v[232:233], v[196:197], v[6:7], v[232:233]
	v_pk_fma_f32 v[234:235], v[196:197], v[2:3], v[234:235]
	v_pk_fma_f32 v[236:237], v[196:197], v[10:11], v[236:237]
	v_fmac_f32_dpp v232, v10, v188 row_ror:1 row_mask:0xf bank_mask:0xf
	v_fmac_f32_dpp v233, v11, v189 row_ror:1 row_mask:0xf bank_mask:0xf
	v_fmac_f32_dpp v238, v14, v196 row_ror:15 row_mask:0xf bank_mask:0xf
	v_fmac_f32_dpp v239, v15, v197 row_ror:15 row_mask:0xf bank_mask:0xf
	v_pk_mul_f32 v[232:233], v[232:233], v[30:31]
	v_pk_mul_f32 v[234:235], v[234:235], v[26:27]
	v_pk_mul_f32 v[236:237], v[236:237], v[18:19]
	v_pk_mul_f32 v[238:239], v[238:239], v[22:23]
	v_cvt_pk_bf16_f32 v80, v232, v233
	v_cvt_pk_bf16_f32 v72, v234, v235
	v_cvt_pk_bf16_f32 v68, v236, v237
	v_cvt_pk_bf16_f32 v76, v238, v239
	v_pk_fma_f32 v[232:233], v[194:195], v[16:17], v[202:203]
	v_pk_fma_f32 v[234:235], v[194:195], v[8:9], v[202:203]
	v_pk_fma_f32 v[236:237], v[194:195], v[4:5], v[202:203]
	v_pk_fma_f32 v[238:239], v[194:195], v[12:13], v[202:203]
	v_pk_fma_f32 v[234:235], v[190:191], v[16:17], v[234:235]
	v_pk_fma_f32 v[236:237], v[190:191], v[8:9], v[236:237]
	v_pk_fma_f32 v[238:239], v[190:191], v[4:5], v[238:239]
	v_pk_fma_f32 v[232:233], v[198:199], v[8:9], v[232:233]
	v_pk_fma_f32 v[234:235], v[198:199], v[4:5], v[234:235]
	v_pk_fma_f32 v[236:237], v[198:199], v[12:13], v[236:237]
	v_fmac_f32_dpp v232, v12, v190 row_ror:1 row_mask:0xf bank_mask:0xf
	v_fmac_f32_dpp v233, v13, v191 row_ror:1 row_mask:0xf bank_mask:0xf
	v_fmac_f32_dpp v238, v16, v198 row_ror:15 row_mask:0xf bank_mask:0xf
	v_fmac_f32_dpp v239, v17, v199 row_ror:15 row_mask:0xf bank_mask:0xf
	v_pk_mul_f32 v[232:233], v[232:233], v[32:33]
	v_pk_mul_f32 v[234:235], v[234:235], v[28:29]
	v_pk_mul_f32 v[236:237], v[236:237], v[20:21]
	v_pk_mul_f32 v[238:239], v[238:239], v[24:25]
	v_cvt_pk_bf16_f32 v81, v232, v233
	v_cvt_pk_bf16_f32 v73, v234, v235
	v_cvt_pk_bf16_f32 v69, v236, v237
	v_cvt_pk_bf16_f32 v77, v238, v239
	s_add_u32 s16, s74, 0xb0000
	s_addc_u32 s17, s75, 0
	s_not_b64 exec, s[4:5]
	global_store_dwordx4 v245, v[78:81], s[16:17]
	s_mov_b64 exec, -1
	s_add_u32 s16, s74, 0xb1600
	s_addc_u32 s17, s75, 0
	global_store_dwordx4 v245, v[70:73], s[16:17]
	s_add_u32 s16, s74, 0xb2c00
	s_addc_u32 s17, s75, 0
	global_store_dwordx4 v245, v[66:69], s[16:17]
	s_add_u32 s16, s74, 0xb4200
	s_addc_u32 s17, s75, 0
	s_not_b64 exec, s[6:7]
	global_store_dwordx4 v245, v[74:77], s[16:17]
	s_mov_b64 exec, -1
	s_branch .LBB0_451
